# P1/P6 epilogues: the 16 IEEE 1/sqrtf chains replaced by v_rsq_f32 (on top of the P4/P9 prelude fix)
# speedup vs baseline: 1.0078x; 1.0078x over previous
.LBB0_223:
	v_lshl_add_u32 v164, s10, 8, v170
	v_ashrrev_i32_e32 v165, 31, v164
	v_or_b32_e32 v162, 16, v164
	v_lshlrev_b64 v[148:149], 6, v[164:165]
	v_ashrrev_i32_e32 v163, 31, v162
	v_or_b32_e32 v160, 32, v164
	v_lshl_add_u64 v[148:149], v[138:139], 0, v[148:149]
	v_lshlrev_b64 v[150:151], 6, v[162:163]
	v_ashrrev_i32_e32 v161, 31, v160
	v_or_b32_e32 v158, 48, v164
	v_lshl_add_u64 v[150:151], v[138:139], 0, v[150:151]
	global_load_dwordx4 v[166:169], v[148:149], off
	global_load_dwordx4 v[182:185], v[150:151], off
	v_lshlrev_b64 v[148:149], 6, v[160:161]
	v_ashrrev_i32_e32 v159, 31, v158
	v_lshl_add_u64 v[148:149], v[138:139], 0, v[148:149]
	v_lshlrev_b64 v[150:151], 6, v[158:159]
	v_lshl_add_u64 v[150:151], v[138:139], 0, v[150:151]
	global_load_dwordx4 v[186:189], v[148:149], off
	global_load_dwordx4 v[190:193], v[150:151], off
	v_add_u32_e32 v156, 0x80, v164
	v_ashrrev_i32_e32 v157, 31, v156
	v_lshlrev_b64 v[148:149], 6, v[156:157]
	v_add_u32_e32 v154, 0x90, v164
	v_lshl_add_u64 v[148:149], v[138:139], 0, v[148:149]
	v_ashrrev_i32_e32 v155, 31, v154
	global_load_dwordx4 v[194:197], v[148:149], off
	v_lshlrev_b64 v[148:149], 6, v[154:155]
	v_lshl_add_u64 v[148:149], v[138:139], 0, v[148:149]
	global_load_dwordx4 v[198:201], v[148:149], off
	v_and_b32_e32 v148, 64, v176
	v_xor_b32_e32 v137, 16, v176
	v_add_u32_e32 v151, 64, v148
	v_xor_b32_e32 v149, 32, v176
	v_add_u32_e32 v150, 0xa0, v164
	v_cmp_lt_i32_e32 vcc, v137, v151
	v_add_u32_e32 v148, 0xb0, v164
	s_cmp_gt_i32 s8, 7
	v_cndmask_b32_e32 v137, v176, v137, vcc
	v_cmp_lt_i32_e32 vcc, v149, v151
	v_ashrrev_i32_e32 v151, 31, v150
	v_lshlrev_b64 v[152:153], 6, v[150:151]
	v_lshl_add_u64 v[152:153], v[138:139], 0, v[152:153]
	global_load_dwordx4 v[204:207], v[152:153], off
	v_cndmask_b32_e32 v179, v176, v149, vcc
	v_ashrrev_i32_e32 v149, 31, v148
	v_lshlrev_b64 v[152:153], 6, v[148:149]
	v_lshl_add_u64 v[152:153], v[138:139], 0, v[152:153]
	global_load_dwordx4 v[208:211], v[152:153], off
	v_lshlrev_b32_e32 v180, 2, v137
	v_lshlrev_b32_e32 v179, 2, v179
	s_cselect_b64 s[10:11], -1, 0
	s_and_b64 s[50:51], s[10:11], exec
	s_cselect_b32 s20, -8, 0
	s_cselect_b32 s9, 0x8000000, 0
	s_add_i32 s20, s20, s8
	s_add_u32 s50, s58, s9
	s_addc_u32 s51, s59, 0
	s_cmp_lt_i32 s8, 8
	s_waitcnt vmcnt(0)
	v_mov_b32_e32 v152, v167
	v_mov_b32_e32 v153, v168
	v_mov_b32_e32 v167, v169
	v_pk_add_f32 v[152:153], v[152:153], v[166:167]
	v_add_f32_e32 v137, v182, v183
	v_add_f32_e32 v152, v152, v153
	v_add_f32_e32 v167, v186, v187
	v_add_f32_e32 v168, v188, v189
	v_add_f32_e32 v153, v167, v168
	ds_bpermute_b32 v168, v180, v152
	v_add_f32_e32 v166, v184, v185
	v_add_f32_e32 v169, v190, v191
	v_add_f32_e32 v181, v192, v193
	v_add_f32_e32 v137, v137, v166
	s_waitcnt lgkmcnt(0)
	v_add_f32_e32 v152, v152, v168
	v_add_f32_e32 v166, v169, v181
	ds_bpermute_b32 v181, v180, v137
	ds_bpermute_b32 v168, v179, v152
	v_add_f32_e32 v182, v194, v195
	v_add_f32_e32 v183, v196, v197
	v_add_f32_e32 v184, v198, v199
	s_waitcnt lgkmcnt(1)
	v_add_f32_e32 v193, v137, v181
	s_waitcnt lgkmcnt(0)
	v_add_f32_e32 v137, v152, v168
	v_fmamk_f32 v137, v137, 0x3a800000, v177
	v_add_f32_e32 v185, v200, v201
	v_add_f32_e32 v167, v182, v183
	ds_bpermute_b32 v182, v180, v153
	v_add_f32_e32 v169, v184, v185
	ds_bpermute_b32 v183, v180, v166
	ds_bpermute_b32 v184, v180, v167
	s_waitcnt lgkmcnt(2)
	v_add_f32_e32 v191, v153, v182
	v_mov_b64_e32 v[198:199], s[30:31]
	s_waitcnt lgkmcnt(1)
	v_add_f32_e32 v189, v166, v183
	s_waitcnt lgkmcnt(0)
	v_add_f32_e32 v187, v167, v184
	ds_bpermute_b32 v194, v179, v193
	ds_bpermute_b32 v192, v179, v191
	ds_bpermute_b32 v190, v179, v189
	ds_bpermute_b32 v188, v179, v187
	v_rsq_f32_e32 v168, v137
	s_nop 0
	v_pk_mul_f32 v[124:125], v[124:125], v[168:169] op_sel_hi:[1,0]
	v_add_f32_e32 v152, v204, v205
	v_and_b32_e32 v197, 0x7fffffff, v125
	v_and_b32_e32 v196, 0x7fffffff, v124
	v_pk_fma_f32 v[196:197], v[196:197], s[26:27], 1.0 op_sel_hi:[1,0,0]
	v_pk_mul_f32 v[204:205], v[124:125], v[124:125]
	v_rcp_f32_e32 v196, v196
	v_rcp_f32_e32 v197, v197
	v_pk_mul_f32 v[204:205], v[204:205], s[40:41] op_sel_hi:[1,0]
	v_pk_mul_f32 v[126:127], v[126:127], v[168:169] op_sel_hi:[1,0]
	v_exp_f32_e32 v204, v204
	v_pk_fma_f32 v[200:201], v[196:197], s[28:29], v[198:199] op_sel_hi:[1,0,0]
	v_exp_f32_e32 v205, v205
	v_pk_fma_f32 v[200:201], v[196:197], v[200:201], s[34:35] op_sel_hi:[1,1,0]
	ds_bpermute_b32 v137, v180, v169
	v_add_f32_e32 v153, v206, v207
	v_pk_fma_f32 v[200:201], v[196:197], v[200:201], s[36:37] op_sel_hi:[1,1,0]
	v_and_b32_e32 v207, 0x7fffffff, v127
	v_and_b32_e32 v206, 0x7fffffff, v126
	v_pk_fma_f32 v[200:201], v[196:197], v[200:201], s[38:39] op_sel_hi:[1,1,0]
	v_pk_fma_f32 v[206:207], v[206:207], s[26:27], 1.0 op_sel_hi:[1,0,0]
	v_pk_mul_f32 v[196:197], v[196:197], v[200:201]
	v_rcp_f32_e32 v206, v206
	v_rcp_f32_e32 v207, v207
	v_pk_mul_f32 v[196:197], v[204:205], v[196:197]
	v_cmp_gt_f32_e32 vcc, 0, v124
	v_pk_mul_f32 v[204:205], v[124:125], v[196:197]
	v_pk_fma_f32 v[196:197], v[124:125], v[196:197], v[124:125] neg_lo:[1,0,0] neg_hi:[1,0,0]
	s_waitcnt lgkmcnt(0)
	v_add_f32_e32 v185, v169, v137
	v_pk_mul_f32 v[200:201], v[126:127], v[126:127]
	v_cndmask_b32_e32 v137, v196, v204, vcc
	v_cmp_gt_f32_e32 vcc, 0, v125
	v_pk_mul_f32 v[122:123], v[122:123], v[168:169] op_sel_hi:[1,0]
	v_pk_mul_f32 v[120:121], v[120:121], v[168:169] op_sel_hi:[1,0]
	v_cndmask_b32_e32 v169, v197, v205, vcc
	v_pk_fma_f32 v[124:125], v[206:207], s[28:29], v[198:199] op_sel_hi:[1,0,0]
	v_pk_mul_f32 v[196:197], v[200:201], s[40:41] op_sel_hi:[1,0]
	v_pk_fma_f32 v[124:125], v[206:207], v[124:125], s[34:35] op_sel_hi:[1,1,0]
	v_exp_f32_e32 v196, v196
	v_exp_f32_e32 v197, v197
	v_pk_fma_f32 v[124:125], v[206:207], v[124:125], s[36:37] op_sel_hi:[1,1,0]
	v_and_b32_e32 v201, 0x7fffffff, v121
	v_and_b32_e32 v200, 0x7fffffff, v120
	v_pk_fma_f32 v[124:125], v[206:207], v[124:125], s[38:39] op_sel_hi:[1,1,0]
	v_pk_fma_f32 v[200:201], v[200:201], s[26:27], 1.0 op_sel_hi:[1,0,0]
	v_pk_mul_f32 v[124:125], v[206:207], v[124:125]
	v_rcp_f32_e32 v200, v200
	v_rcp_f32_e32 v201, v201
	v_pk_mul_f32 v[124:125], v[196:197], v[124:125]
	v_cmp_gt_f32_e32 vcc, 0, v126
	v_pk_mul_f32 v[196:197], v[126:127], v[124:125]
	v_pk_fma_f32 v[124:125], v[126:127], v[124:125], v[126:127] neg_lo:[1,0,0] neg_hi:[1,0,0]
	v_add_f32_e32 v166, v208, v209
	v_cndmask_b32_e32 v195, v124, v196, vcc
	v_cmp_gt_f32_e32 vcc, 0, v127
	v_pk_mul_f32 v[126:127], v[120:121], v[120:121]
	v_add_f32_e32 v167, v210, v211
	v_cndmask_b32_e32 v204, v125, v197, vcc
	v_pk_fma_f32 v[124:125], v[200:201], s[28:29], v[198:199] op_sel_hi:[1,0,0]
	v_pk_mul_f32 v[126:127], v[126:127], s[40:41] op_sel_hi:[1,0]
	v_pk_fma_f32 v[124:125], v[200:201], v[124:125], s[34:35] op_sel_hi:[1,1,0]
	v_exp_f32_e32 v126, v126
	v_pk_fma_f32 v[124:125], v[200:201], v[124:125], s[36:37] op_sel_hi:[1,1,0]
	v_exp_f32_e32 v127, v127
	v_pk_fma_f32 v[124:125], v[200:201], v[124:125], s[38:39] op_sel_hi:[1,1,0]
	v_add_f32_e32 v152, v152, v153
	v_pk_mul_f32 v[124:125], v[200:201], v[124:125]
	v_and_b32_e32 v201, 0x7fffffff, v123
	v_and_b32_e32 v200, 0x7fffffff, v122
	v_pk_fma_f32 v[200:201], v[200:201], s[26:27], 1.0 op_sel_hi:[1,0,0]
	v_pk_mul_f32 v[124:125], v[126:127], v[124:125]
	v_rcp_f32_e32 v200, v200
	v_rcp_f32_e32 v201, v201
	v_add_f32_e32 v166, v166, v167
	v_pk_mul_f32 v[126:127], v[120:121], v[124:125]
	v_pk_fma_f32 v[124:125], v[120:121], v[124:125], v[120:121] neg_lo:[1,0,0] neg_hi:[1,0,0]
	v_cmp_gt_f32_e32 vcc, 0, v120
	ds_bpermute_b32 v153, v180, v152
	ds_bpermute_b32 v167, v180, v166
	v_pk_mul_f32 v[196:197], v[122:123], v[122:123]
	v_cndmask_b32_e32 v126, v124, v126, vcc
	v_cmp_gt_f32_e32 vcc, 0, v121
	v_pk_fma_f32 v[120:121], v[200:201], s[28:29], v[198:199] op_sel_hi:[1,0,0]
	s_waitcnt lgkmcnt(1)
	v_add_f32_e32 v183, v152, v153
	v_cndmask_b32_e32 v127, v125, v127, vcc
	v_pk_mul_f32 v[124:125], v[196:197], s[40:41] op_sel_hi:[1,0]
	v_pk_fma_f32 v[120:121], v[200:201], v[120:121], s[34:35] op_sel_hi:[1,1,0]
	v_exp_f32_e32 v124, v124
	v_exp_f32_e32 v125, v125
	v_pk_fma_f32 v[120:121], v[200:201], v[120:121], s[36:37] op_sel_hi:[1,1,0]
	s_waitcnt lgkmcnt(0)
	v_add_f32_e32 v181, v166, v167
	v_pk_fma_f32 v[120:121], v[200:201], v[120:121], s[38:39] op_sel_hi:[1,1,0]
	ds_bpermute_b32 v186, v179, v185
	v_pk_mul_f32 v[120:121], v[200:201], v[120:121]
	ds_bpermute_b32 v184, v179, v183
	ds_bpermute_b32 v182, v179, v181
	v_pk_mul_f32 v[120:121], v[124:125], v[120:121]
	v_lshl_or_b32 v152, s20, 8, v172
	v_pk_mul_f32 v[124:125], v[122:123], v[120:121]
	v_pk_fma_f32 v[120:121], v[122:123], v[120:121], v[122:123] neg_lo:[1,0,0] neg_hi:[1,0,0]
	v_cmp_gt_f32_e32 vcc, 0, v122
	v_ashrrev_i32_e32 v153, 31, v152
	v_lshl_add_u64 v[152:153], v[152:153], 1, s[50:51]
	v_cndmask_b32_e32 v124, v120, v124, vcc
	v_cmp_gt_f32_e32 vcc, 0, v123
	v_lshlrev_b64 v[166:167], 12, v[164:165]
	v_lshl_add_u64 v[166:167], v[152:153], 0, v[166:167]
	v_cndmask_b32_e32 v123, v121, v125, vcc
	v_cvt_pk_bf16_f32 v120, v137, v169
	v_cvt_pk_bf16_f32 v121, v195, v204
	v_cvt_pk_bf16_f32 v122, v126, v127
	v_cvt_pk_bf16_f32 v123, v124, v123
	v_mov_b32_e32 v124, 0
	v_mov_b32_e32 v125, 0
	global_store_dwordx4 v[166:167], v[120:123], off
	s_cbranch_scc1 .LBB0_225
	v_and_b32_e32 v125, 16, v120
	v_and_b32_e32 v124, 0xffff0000, v120
	v_lshlrev_b32_e32 v197, 16, v121
	v_lshlrev_b32_e32 v196, 16, v122
	v_and_b32_e32 v126, 0xffff0000, v121
	v_mov_b32_e32 v127, v124
	v_pk_mov_b32 v[204:205], v[196:197], v[124:125] op_sel:[1,0]
	v_lshlrev_b32_e32 v120, 16, v120
	v_and_b32_e32 v198, 0xffff0000, v123
	v_mov_b32_e32 v199, v126
	v_and_b32_e32 v122, 0xffff0000, v122
	v_lshlrev_b32_e32 v200, 16, v123
	v_mov_b32_e32 v123, v197
	v_mov_b32_e32 v121, v126
	v_mov_b32_e32 v201, v126
	v_pk_add_f32 v[206:207], v[126:127], v[204:205]
	v_pk_mul_f32 v[126:127], v[126:127], v[204:205]
	v_pk_add_f32 v[124:125], v[120:121], v[124:125] op_sel_hi:[0,1]
	v_mov_b32_e32 v207, v127
	v_pk_add_f32 v[126:127], v[196:197], v[122:123]
	v_pk_mul_f32 v[204:205], v[196:197], v[196:197]
	v_mov_b32_e32 v123, v198
	v_mul_f32_e32 v125, v120, v120
	v_mov_b32_e32 v127, v205
	v_pk_add_f32 v[204:205], v[198:199], v[200:201]
	v_pk_mul_f32 v[120:121], v[198:199], v[120:121]
	v_mov_b32_e32 v197, v200
	v_pk_mul_f32 v[122:123], v[122:123], v[122:123]
	v_mov_b32_e32 v205, v121
	v_pk_fma_f32 v[122:123], v[196:197], v[196:197], v[122:123]
	v_pk_add_f32 v[124:125], v[124:125], v[206:207]
	v_pk_add_f32 v[120:121], v[126:127], v[204:205]
	v_pk_add_f32 v[122:123], v[122:123], v[122:123] op_sel_hi:[0,1]
	v_pk_add_f32 v[120:121], v[124:125], v[120:121]
	v_mov_b32_e32 v137, v123
	v_pk_add_f32 v[124:125], v[120:121], v[136:137]

.LBB0_229:
	s_nop 0
	v_add_f32_e32 v112, v193, v194
	v_fmamk_f32 v112, v112, 0x3a800000, v177
	v_mov_b64_e32 v[118:119], s[30:31]
	s_waitcnt lgkmcnt(1)
	s_waitcnt lgkmcnt(0)
	v_rsq_f32_e32 v114, v112
	s_nop 0
	v_pk_mul_f32 v[108:109], v[108:109], v[114:115] op_sel_hi:[1,0]
	v_pk_mul_f32 v[110:111], v[110:111], v[114:115] op_sel_hi:[1,0]
	v_and_b32_e32 v117, 0x7fffffff, v109
	v_and_b32_e32 v116, 0x7fffffff, v108
	v_pk_fma_f32 v[116:117], v[116:117], s[26:27], 1.0 op_sel_hi:[1,0,0]
	v_pk_mul_f32 v[122:123], v[108:109], v[108:109]
	v_rcp_f32_e32 v116, v116
	v_rcp_f32_e32 v117, v117
	v_pk_mul_f32 v[122:123], v[122:123], s[40:41] op_sel_hi:[1,0]
	v_and_b32_e32 v125, 0x7fffffff, v111
	v_exp_f32_e32 v122, v122
	v_pk_fma_f32 v[120:121], v[116:117], s[28:29], v[118:119] op_sel_hi:[1,0,0]
	v_exp_f32_e32 v123, v123
	v_pk_fma_f32 v[120:121], v[116:117], v[120:121], s[34:35] op_sel_hi:[1,1,0]
	v_and_b32_e32 v124, 0x7fffffff, v110
	v_pk_fma_f32 v[120:121], v[116:117], v[120:121], s[36:37] op_sel_hi:[1,1,0]
	v_pk_fma_f32 v[124:125], v[124:125], s[26:27], 1.0 op_sel_hi:[1,0,0]
	v_pk_fma_f32 v[120:121], v[116:117], v[120:121], s[38:39] op_sel_hi:[1,1,0]
	v_rcp_f32_e32 v124, v124
	v_pk_mul_f32 v[116:117], v[116:117], v[120:121]
	v_rcp_f32_e32 v125, v125
	v_pk_mul_f32 v[116:117], v[122:123], v[116:117]
	v_cmp_gt_f32_e32 vcc, 0, v108
	v_pk_mul_f32 v[122:123], v[108:109], v[116:117]
	v_pk_fma_f32 v[116:117], v[108:109], v[116:117], v[108:109] neg_lo:[1,0,0] neg_hi:[1,0,0]
	v_pk_mul_f32 v[106:107], v[106:107], v[114:115] op_sel_hi:[1,0]
	v_pk_mul_f32 v[104:105], v[104:105], v[114:115] op_sel_hi:[1,0]
	v_pk_mul_f32 v[120:121], v[110:111], v[110:111]
	v_cndmask_b32_e32 v115, v116, v122, vcc
	v_cmp_gt_f32_e32 vcc, 0, v109
	v_pk_fma_f32 v[108:109], v[124:125], s[28:29], v[118:119] op_sel_hi:[1,0,0]
	v_lshlrev_b64 v[112:113], 12, v[162:163]
	v_cndmask_b32_e32 v122, v117, v123, vcc
	v_pk_mul_f32 v[116:117], v[120:121], s[40:41] op_sel_hi:[1,0]
	v_pk_fma_f32 v[108:109], v[124:125], v[108:109], s[34:35] op_sel_hi:[1,1,0]
	v_exp_f32_e32 v116, v116
	v_exp_f32_e32 v117, v117
	v_pk_fma_f32 v[108:109], v[124:125], v[108:109], s[36:37] op_sel_hi:[1,1,0]
	v_and_b32_e32 v121, 0x7fffffff, v105
	v_and_b32_e32 v120, 0x7fffffff, v104
	v_pk_fma_f32 v[108:109], v[124:125], v[108:109], s[38:39] op_sel_hi:[1,1,0]
	v_pk_fma_f32 v[120:121], v[120:121], s[26:27], 1.0 op_sel_hi:[1,0,0]
	v_pk_mul_f32 v[108:109], v[124:125], v[108:109]
	v_rcp_f32_e32 v120, v120
	v_rcp_f32_e32 v121, v121
	v_pk_mul_f32 v[108:109], v[116:117], v[108:109]
	v_cmp_gt_f32_e32 vcc, 0, v110
	v_pk_mul_f32 v[116:117], v[110:111], v[108:109]
	v_pk_fma_f32 v[108:109], v[110:111], v[108:109], v[110:111] neg_lo:[1,0,0] neg_hi:[1,0,0]
	v_lshl_add_u64 v[112:113], v[152:153], 0, v[112:113]
	v_cndmask_b32_e32 v123, v108, v116, vcc
	v_cmp_gt_f32_e32 vcc, 0, v111
	v_pk_mul_f32 v[110:111], v[104:105], v[104:105]
	s_nop 0
	v_cndmask_b32_e32 v124, v109, v117, vcc
	v_pk_fma_f32 v[108:109], v[120:121], s[28:29], v[118:119] op_sel_hi:[1,0,0]
	v_pk_mul_f32 v[110:111], v[110:111], s[40:41] op_sel_hi:[1,0]
	v_pk_fma_f32 v[108:109], v[120:121], v[108:109], s[34:35] op_sel_hi:[1,1,0]
	v_exp_f32_e32 v110, v110
	v_pk_fma_f32 v[108:109], v[120:121], v[108:109], s[36:37] op_sel_hi:[1,1,0]
	v_exp_f32_e32 v111, v111
	v_pk_fma_f32 v[108:109], v[120:121], v[108:109], s[38:39] op_sel_hi:[1,1,0]
	v_cmp_gt_f32_e32 vcc, 0, v104
	v_pk_mul_f32 v[108:109], v[120:121], v[108:109]
	v_and_b32_e32 v121, 0x7fffffff, v107
	v_and_b32_e32 v120, 0x7fffffff, v106
	v_pk_fma_f32 v[120:121], v[120:121], s[26:27], 1.0 op_sel_hi:[1,0,0]
	v_pk_mul_f32 v[108:109], v[110:111], v[108:109]
	v_rcp_f32_e32 v120, v120
	v_rcp_f32_e32 v121, v121
	v_pk_mul_f32 v[110:111], v[104:105], v[108:109]
	v_pk_fma_f32 v[108:109], v[104:105], v[108:109], v[104:105] neg_lo:[1,0,0] neg_hi:[1,0,0]
	v_pk_mul_f32 v[116:117], v[106:107], v[106:107]
	v_cndmask_b32_e32 v110, v108, v110, vcc
	v_cmp_gt_f32_e32 vcc, 0, v105
	v_pk_fma_f32 v[104:105], v[120:121], s[28:29], v[118:119] op_sel_hi:[1,0,0]
	s_nop 0
	v_cndmask_b32_e32 v111, v109, v111, vcc
	v_pk_mul_f32 v[108:109], v[116:117], s[40:41] op_sel_hi:[1,0]
	v_pk_fma_f32 v[104:105], v[120:121], v[104:105], s[34:35] op_sel_hi:[1,1,0]
	v_exp_f32_e32 v108, v108
	v_exp_f32_e32 v109, v109
	v_pk_fma_f32 v[104:105], v[120:121], v[104:105], s[36:37] op_sel_hi:[1,1,0]
	v_cmp_gt_f32_e32 vcc, 0, v106
	v_pk_fma_f32 v[104:105], v[120:121], v[104:105], s[38:39] op_sel_hi:[1,1,0]
	s_nop 0
	v_pk_mul_f32 v[104:105], v[120:121], v[104:105]
	s_nop 0
	v_pk_mul_f32 v[104:105], v[108:109], v[104:105]
	s_nop 0
	v_pk_mul_f32 v[108:109], v[106:107], v[104:105]
	v_pk_fma_f32 v[104:105], v[106:107], v[104:105], v[106:107] neg_lo:[1,0,0] neg_hi:[1,0,0]
	s_nop 0
	v_cndmask_b32_e32 v108, v104, v108, vcc
	v_cmp_gt_f32_e32 vcc, 0, v107
	v_cvt_pk_bf16_f32 v104, v115, v122
	s_nop 1
	v_cndmask_b32_e32 v107, v105, v109, vcc
	v_cvt_pk_bf16_f32 v105, v123, v124
	v_cvt_pk_bf16_f32 v106, v110, v111
	v_cvt_pk_bf16_f32 v107, v108, v107
	v_mov_b32_e32 v108, 0
	s_and_b64 vcc, exec, s[8:9]
	v_mov_b32_e32 v109, 0
	global_store_dwordx4 v[112:113], v[104:107], off
	s_cbranch_vccnz .LBB0_231
	v_and_b32_e32 v109, 16, v104
	v_and_b32_e32 v108, 0xffff0000, v104
	v_lshlrev_b32_e32 v117, 16, v105
	v_lshlrev_b32_e32 v116, 16, v106
	v_and_b32_e32 v110, 0xffff0000, v105
	v_mov_b32_e32 v111, v108
	v_pk_mov_b32 v[122:123], v[116:117], v[108:109] op_sel:[1,0]
	v_lshlrev_b32_e32 v104, 16, v104
	v_and_b32_e32 v118, 0xffff0000, v107
	v_mov_b32_e32 v119, v110
	v_and_b32_e32 v106, 0xffff0000, v106
	v_lshlrev_b32_e32 v120, 16, v107
	v_mov_b32_e32 v107, v117
	v_mov_b32_e32 v105, v110
	v_mov_b32_e32 v121, v110
	v_pk_add_f32 v[124:125], v[110:111], v[122:123]
	v_pk_mul_f32 v[110:111], v[110:111], v[122:123]
	v_pk_add_f32 v[108:109], v[104:105], v[108:109] op_sel_hi:[0,1]
	v_mov_b32_e32 v125, v111
	v_pk_add_f32 v[110:111], v[116:117], v[106:107]
	v_pk_mul_f32 v[122:123], v[116:117], v[116:117]
	v_mov_b32_e32 v107, v118
	v_mul_f32_e32 v109, v104, v104
	v_mov_b32_e32 v111, v123
	v_pk_add_f32 v[122:123], v[118:119], v[120:121]
	v_pk_mul_f32 v[104:105], v[118:119], v[104:105]
	v_mov_b32_e32 v117, v120
	v_pk_mul_f32 v[106:107], v[106:107], v[106:107]
	v_mov_b32_e32 v123, v105
	v_pk_fma_f32 v[106:107], v[116:117], v[116:117], v[106:107]
	v_pk_add_f32 v[108:109], v[108:109], v[124:125]
	v_pk_add_f32 v[104:105], v[110:111], v[122:123]
	v_pk_add_f32 v[106:107], v[106:107], v[106:107] op_sel_hi:[0,1]
	v_pk_add_f32 v[104:105], v[108:109], v[104:105]
	v_mov_b32_e32 v137, v107
	v_pk_add_f32 v[108:109], v[104:105], v[136:137]

.LBB0_235:
	s_nop 0
	v_add_f32_e32 v96, v191, v192
	v_fmamk_f32 v96, v96, 0x3a800000, v177
	v_mov_b64_e32 v[102:103], s[30:31]
	s_waitcnt lgkmcnt(1)
	s_waitcnt lgkmcnt(0)
	v_rsq_f32_e32 v98, v96
	s_nop 0
	v_pk_mul_f32 v[92:93], v[92:93], v[98:99] op_sel_hi:[1,0]
	v_pk_mul_f32 v[94:95], v[94:95], v[98:99] op_sel_hi:[1,0]
	v_and_b32_e32 v101, 0x7fffffff, v93
	v_and_b32_e32 v100, 0x7fffffff, v92
	v_pk_fma_f32 v[100:101], v[100:101], s[26:27], 1.0 op_sel_hi:[1,0,0]
	v_pk_mul_f32 v[106:107], v[92:93], v[92:93]
	v_rcp_f32_e32 v100, v100
	v_rcp_f32_e32 v101, v101
	v_pk_mul_f32 v[106:107], v[106:107], s[40:41] op_sel_hi:[1,0]
	v_and_b32_e32 v109, 0x7fffffff, v95
	v_exp_f32_e32 v106, v106
	v_pk_fma_f32 v[104:105], v[100:101], s[28:29], v[102:103] op_sel_hi:[1,0,0]
	v_exp_f32_e32 v107, v107
	v_pk_fma_f32 v[104:105], v[100:101], v[104:105], s[34:35] op_sel_hi:[1,1,0]
	v_and_b32_e32 v108, 0x7fffffff, v94
	v_pk_fma_f32 v[104:105], v[100:101], v[104:105], s[36:37] op_sel_hi:[1,1,0]
	v_pk_fma_f32 v[108:109], v[108:109], s[26:27], 1.0 op_sel_hi:[1,0,0]
	v_pk_fma_f32 v[104:105], v[100:101], v[104:105], s[38:39] op_sel_hi:[1,1,0]
	v_rcp_f32_e32 v108, v108
	v_pk_mul_f32 v[100:101], v[100:101], v[104:105]
	v_rcp_f32_e32 v109, v109
	v_pk_mul_f32 v[100:101], v[106:107], v[100:101]
	v_cmp_gt_f32_e32 vcc, 0, v92
	v_pk_mul_f32 v[106:107], v[92:93], v[100:101]
	v_pk_fma_f32 v[100:101], v[92:93], v[100:101], v[92:93] neg_lo:[1,0,0] neg_hi:[1,0,0]
	v_pk_mul_f32 v[90:91], v[90:91], v[98:99] op_sel_hi:[1,0]
	v_pk_mul_f32 v[88:89], v[88:89], v[98:99] op_sel_hi:[1,0]
	v_pk_mul_f32 v[104:105], v[94:95], v[94:95]
	v_cndmask_b32_e32 v99, v100, v106, vcc
	v_cmp_gt_f32_e32 vcc, 0, v93
	v_pk_fma_f32 v[92:93], v[108:109], s[28:29], v[102:103] op_sel_hi:[1,0,0]
	v_lshlrev_b64 v[96:97], 12, v[160:161]
	v_cndmask_b32_e32 v106, v101, v107, vcc
	v_pk_mul_f32 v[100:101], v[104:105], s[40:41] op_sel_hi:[1,0]
	v_pk_fma_f32 v[92:93], v[108:109], v[92:93], s[34:35] op_sel_hi:[1,1,0]
	v_exp_f32_e32 v100, v100
	v_exp_f32_e32 v101, v101
	v_pk_fma_f32 v[92:93], v[108:109], v[92:93], s[36:37] op_sel_hi:[1,1,0]
	v_and_b32_e32 v105, 0x7fffffff, v89
	v_and_b32_e32 v104, 0x7fffffff, v88
	v_pk_fma_f32 v[92:93], v[108:109], v[92:93], s[38:39] op_sel_hi:[1,1,0]
	v_pk_fma_f32 v[104:105], v[104:105], s[26:27], 1.0 op_sel_hi:[1,0,0]
	v_pk_mul_f32 v[92:93], v[108:109], v[92:93]
	v_rcp_f32_e32 v104, v104
	v_rcp_f32_e32 v105, v105
	v_pk_mul_f32 v[92:93], v[100:101], v[92:93]
	v_cmp_gt_f32_e32 vcc, 0, v94
	v_pk_mul_f32 v[100:101], v[94:95], v[92:93]
	v_pk_fma_f32 v[92:93], v[94:95], v[92:93], v[94:95] neg_lo:[1,0,0] neg_hi:[1,0,0]
	v_lshl_add_u64 v[96:97], v[152:153], 0, v[96:97]
	v_cndmask_b32_e32 v107, v92, v100, vcc
	v_cmp_gt_f32_e32 vcc, 0, v95
	v_pk_mul_f32 v[94:95], v[88:89], v[88:89]
	s_nop 0
	v_cndmask_b32_e32 v108, v93, v101, vcc
	v_pk_fma_f32 v[92:93], v[104:105], s[28:29], v[102:103] op_sel_hi:[1,0,0]
	v_pk_mul_f32 v[94:95], v[94:95], s[40:41] op_sel_hi:[1,0]
	v_pk_fma_f32 v[92:93], v[104:105], v[92:93], s[34:35] op_sel_hi:[1,1,0]
	v_exp_f32_e32 v94, v94
	v_pk_fma_f32 v[92:93], v[104:105], v[92:93], s[36:37] op_sel_hi:[1,1,0]
	v_exp_f32_e32 v95, v95
	v_pk_fma_f32 v[92:93], v[104:105], v[92:93], s[38:39] op_sel_hi:[1,1,0]
	v_cmp_gt_f32_e32 vcc, 0, v88
	v_pk_mul_f32 v[92:93], v[104:105], v[92:93]
	v_and_b32_e32 v105, 0x7fffffff, v91
	v_and_b32_e32 v104, 0x7fffffff, v90
	v_pk_fma_f32 v[104:105], v[104:105], s[26:27], 1.0 op_sel_hi:[1,0,0]
	v_pk_mul_f32 v[92:93], v[94:95], v[92:93]
	v_rcp_f32_e32 v104, v104
	v_rcp_f32_e32 v105, v105
	v_pk_mul_f32 v[94:95], v[88:89], v[92:93]
	v_pk_fma_f32 v[92:93], v[88:89], v[92:93], v[88:89] neg_lo:[1,0,0] neg_hi:[1,0,0]
	v_pk_mul_f32 v[100:101], v[90:91], v[90:91]
	v_cndmask_b32_e32 v94, v92, v94, vcc
	v_cmp_gt_f32_e32 vcc, 0, v89
	v_pk_fma_f32 v[88:89], v[104:105], s[28:29], v[102:103] op_sel_hi:[1,0,0]
	s_nop 0
	v_cndmask_b32_e32 v95, v93, v95, vcc
	v_pk_mul_f32 v[92:93], v[100:101], s[40:41] op_sel_hi:[1,0]
	v_pk_fma_f32 v[88:89], v[104:105], v[88:89], s[34:35] op_sel_hi:[1,1,0]
	v_exp_f32_e32 v92, v92
	v_exp_f32_e32 v93, v93
	v_pk_fma_f32 v[88:89], v[104:105], v[88:89], s[36:37] op_sel_hi:[1,1,0]
	v_cmp_gt_f32_e32 vcc, 0, v90
	v_pk_fma_f32 v[88:89], v[104:105], v[88:89], s[38:39] op_sel_hi:[1,1,0]
	s_nop 0
	v_pk_mul_f32 v[88:89], v[104:105], v[88:89]
	s_nop 0
	v_pk_mul_f32 v[88:89], v[92:93], v[88:89]
	s_nop 0
	v_pk_mul_f32 v[92:93], v[90:91], v[88:89]
	v_pk_fma_f32 v[88:89], v[90:91], v[88:89], v[90:91] neg_lo:[1,0,0] neg_hi:[1,0,0]
	s_nop 0
	v_cndmask_b32_e32 v92, v88, v92, vcc
	v_cmp_gt_f32_e32 vcc, 0, v91
	v_cvt_pk_bf16_f32 v88, v99, v106
	s_nop 1
	v_cndmask_b32_e32 v91, v89, v93, vcc
	v_cvt_pk_bf16_f32 v89, v107, v108
	v_cvt_pk_bf16_f32 v90, v94, v95
	v_cvt_pk_bf16_f32 v91, v92, v91
	v_mov_b32_e32 v92, 0
	s_and_b64 vcc, exec, s[8:9]
	v_mov_b32_e32 v93, 0
	global_store_dwordx4 v[96:97], v[88:91], off
	s_cbranch_vccnz .LBB0_237
	v_and_b32_e32 v93, 16, v88
	v_and_b32_e32 v92, 0xffff0000, v88
	v_lshlrev_b32_e32 v101, 16, v89
	v_lshlrev_b32_e32 v100, 16, v90
	v_and_b32_e32 v94, 0xffff0000, v89
	v_mov_b32_e32 v95, v92
	v_pk_mov_b32 v[106:107], v[100:101], v[92:93] op_sel:[1,0]
	v_lshlrev_b32_e32 v88, 16, v88
	v_and_b32_e32 v102, 0xffff0000, v91
	v_mov_b32_e32 v103, v94
	v_and_b32_e32 v90, 0xffff0000, v90
	v_lshlrev_b32_e32 v104, 16, v91
	v_mov_b32_e32 v91, v101
	v_mov_b32_e32 v89, v94
	v_mov_b32_e32 v105, v94
	v_pk_add_f32 v[108:109], v[94:95], v[106:107]
	v_pk_mul_f32 v[94:95], v[94:95], v[106:107]
	v_pk_add_f32 v[92:93], v[88:89], v[92:93] op_sel_hi:[0,1]
	v_mov_b32_e32 v109, v95
	v_pk_add_f32 v[94:95], v[100:101], v[90:91]
	v_pk_mul_f32 v[106:107], v[100:101], v[100:101]
	v_mov_b32_e32 v91, v102
	v_mul_f32_e32 v93, v88, v88
	v_mov_b32_e32 v95, v107
	v_pk_add_f32 v[106:107], v[102:103], v[104:105]
	v_pk_mul_f32 v[88:89], v[102:103], v[88:89]
	v_mov_b32_e32 v101, v104
	v_pk_mul_f32 v[90:91], v[90:91], v[90:91]
	v_mov_b32_e32 v107, v89
	v_pk_fma_f32 v[90:91], v[100:101], v[100:101], v[90:91]
	v_pk_add_f32 v[92:93], v[92:93], v[108:109]
	v_pk_add_f32 v[88:89], v[94:95], v[106:107]
	v_pk_add_f32 v[90:91], v[90:91], v[90:91] op_sel_hi:[0,1]
	v_pk_add_f32 v[88:89], v[92:93], v[88:89]
	v_mov_b32_e32 v137, v91
	v_pk_add_f32 v[92:93], v[88:89], v[136:137]

.LBB0_241:
	s_nop 0
	v_add_f32_e32 v80, v189, v190
	v_fmamk_f32 v80, v80, 0x3a800000, v177
	v_mov_b64_e32 v[86:87], s[30:31]
	s_waitcnt lgkmcnt(1)
	s_waitcnt lgkmcnt(0)
	v_rsq_f32_e32 v82, v80
	s_nop 0
	v_pk_mul_f32 v[76:77], v[76:77], v[82:83] op_sel_hi:[1,0]
	v_pk_mul_f32 v[78:79], v[78:79], v[82:83] op_sel_hi:[1,0]
	v_and_b32_e32 v85, 0x7fffffff, v77
	v_and_b32_e32 v84, 0x7fffffff, v76
	v_pk_fma_f32 v[84:85], v[84:85], s[26:27], 1.0 op_sel_hi:[1,0,0]
	v_pk_mul_f32 v[90:91], v[76:77], v[76:77]
	v_rcp_f32_e32 v84, v84
	v_rcp_f32_e32 v85, v85
	v_pk_mul_f32 v[90:91], v[90:91], s[40:41] op_sel_hi:[1,0]
	v_and_b32_e32 v93, 0x7fffffff, v79
	v_exp_f32_e32 v90, v90
	v_pk_fma_f32 v[88:89], v[84:85], s[28:29], v[86:87] op_sel_hi:[1,0,0]
	v_exp_f32_e32 v91, v91
	v_pk_fma_f32 v[88:89], v[84:85], v[88:89], s[34:35] op_sel_hi:[1,1,0]
	v_and_b32_e32 v92, 0x7fffffff, v78
	v_pk_fma_f32 v[88:89], v[84:85], v[88:89], s[36:37] op_sel_hi:[1,1,0]
	v_pk_fma_f32 v[92:93], v[92:93], s[26:27], 1.0 op_sel_hi:[1,0,0]
	v_pk_fma_f32 v[88:89], v[84:85], v[88:89], s[38:39] op_sel_hi:[1,1,0]
	v_rcp_f32_e32 v92, v92
	v_pk_mul_f32 v[84:85], v[84:85], v[88:89]
	v_rcp_f32_e32 v93, v93
	v_pk_mul_f32 v[84:85], v[90:91], v[84:85]
	v_cmp_gt_f32_e32 vcc, 0, v76
	v_pk_mul_f32 v[90:91], v[76:77], v[84:85]
	v_pk_fma_f32 v[84:85], v[76:77], v[84:85], v[76:77] neg_lo:[1,0,0] neg_hi:[1,0,0]
	v_pk_mul_f32 v[74:75], v[74:75], v[82:83] op_sel_hi:[1,0]
	v_pk_mul_f32 v[72:73], v[72:73], v[82:83] op_sel_hi:[1,0]
	v_pk_mul_f32 v[88:89], v[78:79], v[78:79]
	v_cndmask_b32_e32 v83, v84, v90, vcc
	v_cmp_gt_f32_e32 vcc, 0, v77
	v_pk_fma_f32 v[76:77], v[92:93], s[28:29], v[86:87] op_sel_hi:[1,0,0]
	v_lshlrev_b64 v[80:81], 12, v[158:159]
	v_cndmask_b32_e32 v90, v85, v91, vcc
	v_pk_mul_f32 v[84:85], v[88:89], s[40:41] op_sel_hi:[1,0]
	v_pk_fma_f32 v[76:77], v[92:93], v[76:77], s[34:35] op_sel_hi:[1,1,0]
	v_exp_f32_e32 v84, v84
	v_exp_f32_e32 v85, v85
	v_pk_fma_f32 v[76:77], v[92:93], v[76:77], s[36:37] op_sel_hi:[1,1,0]
	v_and_b32_e32 v89, 0x7fffffff, v73
	v_and_b32_e32 v88, 0x7fffffff, v72
	v_pk_fma_f32 v[76:77], v[92:93], v[76:77], s[38:39] op_sel_hi:[1,1,0]
	v_pk_fma_f32 v[88:89], v[88:89], s[26:27], 1.0 op_sel_hi:[1,0,0]
	v_pk_mul_f32 v[76:77], v[92:93], v[76:77]
	v_rcp_f32_e32 v88, v88
	v_rcp_f32_e32 v89, v89
	v_pk_mul_f32 v[76:77], v[84:85], v[76:77]
	v_cmp_gt_f32_e32 vcc, 0, v78
	v_pk_mul_f32 v[84:85], v[78:79], v[76:77]
	v_pk_fma_f32 v[76:77], v[78:79], v[76:77], v[78:79] neg_lo:[1,0,0] neg_hi:[1,0,0]
	v_lshl_add_u64 v[80:81], v[152:153], 0, v[80:81]
	v_cndmask_b32_e32 v91, v76, v84, vcc
	v_cmp_gt_f32_e32 vcc, 0, v79
	v_pk_mul_f32 v[78:79], v[72:73], v[72:73]
	s_nop 0
	v_cndmask_b32_e32 v92, v77, v85, vcc
	v_pk_fma_f32 v[76:77], v[88:89], s[28:29], v[86:87] op_sel_hi:[1,0,0]
	v_pk_mul_f32 v[78:79], v[78:79], s[40:41] op_sel_hi:[1,0]
	v_pk_fma_f32 v[76:77], v[88:89], v[76:77], s[34:35] op_sel_hi:[1,1,0]
	v_exp_f32_e32 v78, v78
	v_pk_fma_f32 v[76:77], v[88:89], v[76:77], s[36:37] op_sel_hi:[1,1,0]
	v_exp_f32_e32 v79, v79
	v_pk_fma_f32 v[76:77], v[88:89], v[76:77], s[38:39] op_sel_hi:[1,1,0]
	v_cmp_gt_f32_e32 vcc, 0, v72
	v_pk_mul_f32 v[76:77], v[88:89], v[76:77]
	v_and_b32_e32 v89, 0x7fffffff, v75
	v_and_b32_e32 v88, 0x7fffffff, v74
	v_pk_fma_f32 v[88:89], v[88:89], s[26:27], 1.0 op_sel_hi:[1,0,0]
	v_pk_mul_f32 v[76:77], v[78:79], v[76:77]
	v_rcp_f32_e32 v88, v88
	v_rcp_f32_e32 v89, v89
	v_pk_mul_f32 v[78:79], v[72:73], v[76:77]
	v_pk_fma_f32 v[76:77], v[72:73], v[76:77], v[72:73] neg_lo:[1,0,0] neg_hi:[1,0,0]
	v_pk_mul_f32 v[84:85], v[74:75], v[74:75]
	v_cndmask_b32_e32 v78, v76, v78, vcc
	v_cmp_gt_f32_e32 vcc, 0, v73
	v_pk_fma_f32 v[72:73], v[88:89], s[28:29], v[86:87] op_sel_hi:[1,0,0]
	s_nop 0
	v_cndmask_b32_e32 v79, v77, v79, vcc
	v_pk_mul_f32 v[76:77], v[84:85], s[40:41] op_sel_hi:[1,0]
	v_pk_fma_f32 v[72:73], v[88:89], v[72:73], s[34:35] op_sel_hi:[1,1,0]
	v_exp_f32_e32 v76, v76
	v_exp_f32_e32 v77, v77
	v_pk_fma_f32 v[72:73], v[88:89], v[72:73], s[36:37] op_sel_hi:[1,1,0]
	v_cmp_gt_f32_e32 vcc, 0, v74
	v_pk_fma_f32 v[72:73], v[88:89], v[72:73], s[38:39] op_sel_hi:[1,1,0]
	s_nop 0
	v_pk_mul_f32 v[72:73], v[88:89], v[72:73]
	s_nop 0
	v_pk_mul_f32 v[72:73], v[76:77], v[72:73]
	s_nop 0
	v_pk_mul_f32 v[76:77], v[74:75], v[72:73]
	v_pk_fma_f32 v[72:73], v[74:75], v[72:73], v[74:75] neg_lo:[1,0,0] neg_hi:[1,0,0]
	s_nop 0
	v_cndmask_b32_e32 v76, v72, v76, vcc
	v_cmp_gt_f32_e32 vcc, 0, v75
	v_cvt_pk_bf16_f32 v72, v83, v90
	s_nop 1
	v_cndmask_b32_e32 v75, v73, v77, vcc
	v_cvt_pk_bf16_f32 v73, v91, v92
	v_cvt_pk_bf16_f32 v74, v78, v79
	v_cvt_pk_bf16_f32 v75, v76, v75
	v_mov_b32_e32 v76, 0
	s_and_b64 vcc, exec, s[8:9]
	v_mov_b32_e32 v77, 0
	global_store_dwordx4 v[80:81], v[72:75], off
	s_cbranch_vccnz .LBB0_243
	v_and_b32_e32 v77, 16, v72
	v_and_b32_e32 v76, 0xffff0000, v72
	v_lshlrev_b32_e32 v85, 16, v73
	v_lshlrev_b32_e32 v84, 16, v74
	v_and_b32_e32 v78, 0xffff0000, v73
	v_mov_b32_e32 v79, v76
	v_pk_mov_b32 v[90:91], v[84:85], v[76:77] op_sel:[1,0]
	v_lshlrev_b32_e32 v72, 16, v72
	v_and_b32_e32 v86, 0xffff0000, v75
	v_mov_b32_e32 v87, v78
	v_and_b32_e32 v74, 0xffff0000, v74
	v_lshlrev_b32_e32 v88, 16, v75
	v_mov_b32_e32 v75, v85
	v_mov_b32_e32 v73, v78
	v_mov_b32_e32 v89, v78
	v_pk_add_f32 v[92:93], v[78:79], v[90:91]
	v_pk_mul_f32 v[78:79], v[78:79], v[90:91]
	v_pk_add_f32 v[76:77], v[72:73], v[76:77] op_sel_hi:[0,1]
	v_mov_b32_e32 v93, v79
	v_pk_add_f32 v[78:79], v[84:85], v[74:75]
	v_pk_mul_f32 v[90:91], v[84:85], v[84:85]
	v_mov_b32_e32 v75, v86
	v_mul_f32_e32 v77, v72, v72
	v_mov_b32_e32 v79, v91
	v_pk_add_f32 v[90:91], v[86:87], v[88:89]
	v_pk_mul_f32 v[72:73], v[86:87], v[72:73]
	v_mov_b32_e32 v85, v88
	v_pk_mul_f32 v[74:75], v[74:75], v[74:75]
	v_mov_b32_e32 v91, v73
	v_pk_fma_f32 v[74:75], v[84:85], v[84:85], v[74:75]
	v_pk_add_f32 v[76:77], v[76:77], v[92:93]
	v_pk_add_f32 v[72:73], v[78:79], v[90:91]
	v_pk_add_f32 v[74:75], v[74:75], v[74:75] op_sel_hi:[0,1]
	v_pk_add_f32 v[72:73], v[76:77], v[72:73]
	v_mov_b32_e32 v137, v75
	v_pk_add_f32 v[76:77], v[72:73], v[136:137]

.LBB0_247:
	s_nop 0
	v_add_f32_e32 v64, v187, v188
	v_fmamk_f32 v64, v64, 0x3a800000, v177
	v_mov_b64_e32 v[70:71], s[30:31]
	s_waitcnt lgkmcnt(1)
	s_waitcnt lgkmcnt(0)
	v_rsq_f32_e32 v66, v64
	s_nop 0
	v_pk_mul_f32 v[60:61], v[60:61], v[66:67] op_sel_hi:[1,0]
	v_pk_mul_f32 v[62:63], v[62:63], v[66:67] op_sel_hi:[1,0]
	v_and_b32_e32 v69, 0x7fffffff, v61
	v_and_b32_e32 v68, 0x7fffffff, v60
	v_pk_fma_f32 v[68:69], v[68:69], s[26:27], 1.0 op_sel_hi:[1,0,0]
	v_pk_mul_f32 v[74:75], v[60:61], v[60:61]
	v_rcp_f32_e32 v68, v68
	v_rcp_f32_e32 v69, v69
	v_pk_mul_f32 v[74:75], v[74:75], s[40:41] op_sel_hi:[1,0]
	v_and_b32_e32 v77, 0x7fffffff, v63
	v_exp_f32_e32 v74, v74
	v_pk_fma_f32 v[72:73], v[68:69], s[28:29], v[70:71] op_sel_hi:[1,0,0]
	v_exp_f32_e32 v75, v75
	v_pk_fma_f32 v[72:73], v[68:69], v[72:73], s[34:35] op_sel_hi:[1,1,0]
	v_and_b32_e32 v76, 0x7fffffff, v62
	v_pk_fma_f32 v[72:73], v[68:69], v[72:73], s[36:37] op_sel_hi:[1,1,0]
	v_pk_fma_f32 v[76:77], v[76:77], s[26:27], 1.0 op_sel_hi:[1,0,0]
	v_pk_fma_f32 v[72:73], v[68:69], v[72:73], s[38:39] op_sel_hi:[1,1,0]
	v_rcp_f32_e32 v76, v76
	v_pk_mul_f32 v[68:69], v[68:69], v[72:73]
	v_rcp_f32_e32 v77, v77
	v_pk_mul_f32 v[68:69], v[74:75], v[68:69]
	v_cmp_gt_f32_e32 vcc, 0, v60
	v_pk_mul_f32 v[74:75], v[60:61], v[68:69]
	v_pk_fma_f32 v[68:69], v[60:61], v[68:69], v[60:61] neg_lo:[1,0,0] neg_hi:[1,0,0]
	v_pk_mul_f32 v[58:59], v[58:59], v[66:67] op_sel_hi:[1,0]
	v_pk_mul_f32 v[56:57], v[56:57], v[66:67] op_sel_hi:[1,0]
	v_pk_mul_f32 v[72:73], v[62:63], v[62:63]
	v_cndmask_b32_e32 v67, v68, v74, vcc
	v_cmp_gt_f32_e32 vcc, 0, v61
	v_pk_fma_f32 v[60:61], v[76:77], s[28:29], v[70:71] op_sel_hi:[1,0,0]
	v_lshlrev_b64 v[64:65], 12, v[156:157]
	v_cndmask_b32_e32 v74, v69, v75, vcc
	v_pk_mul_f32 v[68:69], v[72:73], s[40:41] op_sel_hi:[1,0]
	v_pk_fma_f32 v[60:61], v[76:77], v[60:61], s[34:35] op_sel_hi:[1,1,0]
	v_exp_f32_e32 v68, v68
	v_exp_f32_e32 v69, v69
	v_pk_fma_f32 v[60:61], v[76:77], v[60:61], s[36:37] op_sel_hi:[1,1,0]
	v_and_b32_e32 v73, 0x7fffffff, v57
	v_and_b32_e32 v72, 0x7fffffff, v56
	v_pk_fma_f32 v[60:61], v[76:77], v[60:61], s[38:39] op_sel_hi:[1,1,0]
	v_pk_fma_f32 v[72:73], v[72:73], s[26:27], 1.0 op_sel_hi:[1,0,0]
	v_pk_mul_f32 v[60:61], v[76:77], v[60:61]
	v_rcp_f32_e32 v72, v72
	v_rcp_f32_e32 v73, v73
	v_pk_mul_f32 v[60:61], v[68:69], v[60:61]
	v_cmp_gt_f32_e32 vcc, 0, v62
	v_pk_mul_f32 v[68:69], v[62:63], v[60:61]
	v_pk_fma_f32 v[60:61], v[62:63], v[60:61], v[62:63] neg_lo:[1,0,0] neg_hi:[1,0,0]
	v_lshl_add_u64 v[64:65], v[152:153], 0, v[64:65]
	v_cndmask_b32_e32 v75, v60, v68, vcc
	v_cmp_gt_f32_e32 vcc, 0, v63
	v_pk_mul_f32 v[62:63], v[56:57], v[56:57]
	s_nop 0
	v_cndmask_b32_e32 v76, v61, v69, vcc
	v_pk_fma_f32 v[60:61], v[72:73], s[28:29], v[70:71] op_sel_hi:[1,0,0]
	v_pk_mul_f32 v[62:63], v[62:63], s[40:41] op_sel_hi:[1,0]
	v_pk_fma_f32 v[60:61], v[72:73], v[60:61], s[34:35] op_sel_hi:[1,1,0]
	v_exp_f32_e32 v62, v62
	v_pk_fma_f32 v[60:61], v[72:73], v[60:61], s[36:37] op_sel_hi:[1,1,0]
	v_exp_f32_e32 v63, v63
	v_pk_fma_f32 v[60:61], v[72:73], v[60:61], s[38:39] op_sel_hi:[1,1,0]
	v_cmp_gt_f32_e32 vcc, 0, v56
	v_pk_mul_f32 v[60:61], v[72:73], v[60:61]
	v_and_b32_e32 v73, 0x7fffffff, v59
	v_and_b32_e32 v72, 0x7fffffff, v58
	v_pk_fma_f32 v[72:73], v[72:73], s[26:27], 1.0 op_sel_hi:[1,0,0]
	v_pk_mul_f32 v[60:61], v[62:63], v[60:61]
	v_rcp_f32_e32 v72, v72
	v_rcp_f32_e32 v73, v73
	v_pk_mul_f32 v[62:63], v[56:57], v[60:61]
	v_pk_fma_f32 v[60:61], v[56:57], v[60:61], v[56:57] neg_lo:[1,0,0] neg_hi:[1,0,0]
	v_pk_mul_f32 v[68:69], v[58:59], v[58:59]
	v_cndmask_b32_e32 v62, v60, v62, vcc
	v_cmp_gt_f32_e32 vcc, 0, v57
	v_pk_fma_f32 v[56:57], v[72:73], s[28:29], v[70:71] op_sel_hi:[1,0,0]
	s_nop 0
	v_cndmask_b32_e32 v63, v61, v63, vcc
	v_pk_mul_f32 v[60:61], v[68:69], s[40:41] op_sel_hi:[1,0]
	v_pk_fma_f32 v[56:57], v[72:73], v[56:57], s[34:35] op_sel_hi:[1,1,0]
	v_exp_f32_e32 v60, v60
	v_exp_f32_e32 v61, v61
	v_pk_fma_f32 v[56:57], v[72:73], v[56:57], s[36:37] op_sel_hi:[1,1,0]
	v_cmp_gt_f32_e32 vcc, 0, v58
	v_pk_fma_f32 v[56:57], v[72:73], v[56:57], s[38:39] op_sel_hi:[1,1,0]
	s_nop 0
	v_pk_mul_f32 v[56:57], v[72:73], v[56:57]
	s_nop 0
	v_pk_mul_f32 v[56:57], v[60:61], v[56:57]
	s_nop 0
	v_pk_mul_f32 v[60:61], v[58:59], v[56:57]
	v_pk_fma_f32 v[56:57], v[58:59], v[56:57], v[58:59] neg_lo:[1,0,0] neg_hi:[1,0,0]
	s_nop 0
	v_cndmask_b32_e32 v60, v56, v60, vcc
	v_cmp_gt_f32_e32 vcc, 0, v59
	v_cvt_pk_bf16_f32 v56, v67, v74
	s_nop 1
	v_cndmask_b32_e32 v59, v57, v61, vcc
	v_cvt_pk_bf16_f32 v57, v75, v76
	v_cvt_pk_bf16_f32 v58, v62, v63
	v_cvt_pk_bf16_f32 v59, v60, v59
	v_mov_b32_e32 v60, 0
	s_and_b64 vcc, exec, s[8:9]
	v_mov_b32_e32 v61, 0
	global_store_dwordx4 v[64:65], v[56:59], off
	s_cbranch_vccnz .LBB0_249
	v_and_b32_e32 v61, 16, v56
	v_and_b32_e32 v60, 0xffff0000, v56
	v_lshlrev_b32_e32 v69, 16, v57
	v_lshlrev_b32_e32 v68, 16, v58
	v_and_b32_e32 v62, 0xffff0000, v57
	v_mov_b32_e32 v63, v60
	v_pk_mov_b32 v[74:75], v[68:69], v[60:61] op_sel:[1,0]
	v_lshlrev_b32_e32 v56, 16, v56
	v_and_b32_e32 v70, 0xffff0000, v59
	v_mov_b32_e32 v71, v62
	v_and_b32_e32 v58, 0xffff0000, v58
	v_lshlrev_b32_e32 v72, 16, v59
	v_mov_b32_e32 v59, v69
	v_mov_b32_e32 v57, v62
	v_mov_b32_e32 v73, v62
	v_pk_add_f32 v[76:77], v[62:63], v[74:75]
	v_pk_mul_f32 v[62:63], v[62:63], v[74:75]
	v_pk_add_f32 v[60:61], v[56:57], v[60:61] op_sel_hi:[0,1]
	v_mov_b32_e32 v77, v63
	v_pk_add_f32 v[62:63], v[68:69], v[58:59]
	v_pk_mul_f32 v[74:75], v[68:69], v[68:69]
	v_mov_b32_e32 v59, v70
	v_mul_f32_e32 v61, v56, v56
	v_mov_b32_e32 v63, v75
	v_pk_add_f32 v[74:75], v[70:71], v[72:73]
	v_pk_mul_f32 v[56:57], v[70:71], v[56:57]
	v_mov_b32_e32 v69, v72
	v_pk_mul_f32 v[58:59], v[58:59], v[58:59]
	v_mov_b32_e32 v75, v57
	v_pk_fma_f32 v[58:59], v[68:69], v[68:69], v[58:59]
	v_pk_add_f32 v[60:61], v[60:61], v[76:77]
	v_pk_add_f32 v[56:57], v[62:63], v[74:75]
	v_pk_add_f32 v[58:59], v[58:59], v[58:59] op_sel_hi:[0,1]
	v_pk_add_f32 v[56:57], v[60:61], v[56:57]
	v_mov_b32_e32 v137, v59
	v_pk_add_f32 v[60:61], v[56:57], v[136:137]

.LBB0_253:
	s_nop 0
	v_add_f32_e32 v48, v185, v186
	v_fmamk_f32 v48, v48, 0x3a800000, v177
	v_mov_b64_e32 v[54:55], s[30:31]
	s_waitcnt lgkmcnt(1)
	s_waitcnt lgkmcnt(0)
	v_rsq_f32_e32 v50, v48
	s_nop 0
	v_pk_mul_f32 v[44:45], v[44:45], v[50:51] op_sel_hi:[1,0]
	v_pk_mul_f32 v[46:47], v[46:47], v[50:51] op_sel_hi:[1,0]
	v_and_b32_e32 v53, 0x7fffffff, v45
	v_and_b32_e32 v52, 0x7fffffff, v44
	v_pk_fma_f32 v[52:53], v[52:53], s[26:27], 1.0 op_sel_hi:[1,0,0]
	v_pk_mul_f32 v[58:59], v[44:45], v[44:45]
	v_rcp_f32_e32 v52, v52
	v_rcp_f32_e32 v53, v53
	v_pk_mul_f32 v[58:59], v[58:59], s[40:41] op_sel_hi:[1,0]
	v_and_b32_e32 v61, 0x7fffffff, v47
	v_exp_f32_e32 v58, v58
	v_pk_fma_f32 v[56:57], v[52:53], s[28:29], v[54:55] op_sel_hi:[1,0,0]
	v_exp_f32_e32 v59, v59
	v_pk_fma_f32 v[56:57], v[52:53], v[56:57], s[34:35] op_sel_hi:[1,1,0]
	v_and_b32_e32 v60, 0x7fffffff, v46
	v_pk_fma_f32 v[56:57], v[52:53], v[56:57], s[36:37] op_sel_hi:[1,1,0]
	v_pk_fma_f32 v[60:61], v[60:61], s[26:27], 1.0 op_sel_hi:[1,0,0]
	v_pk_fma_f32 v[56:57], v[52:53], v[56:57], s[38:39] op_sel_hi:[1,1,0]
	v_rcp_f32_e32 v60, v60
	v_pk_mul_f32 v[52:53], v[52:53], v[56:57]
	v_rcp_f32_e32 v61, v61
	v_pk_mul_f32 v[52:53], v[58:59], v[52:53]
	v_cmp_gt_f32_e32 vcc, 0, v44
	v_pk_mul_f32 v[58:59], v[44:45], v[52:53]
	v_pk_fma_f32 v[52:53], v[44:45], v[52:53], v[44:45] neg_lo:[1,0,0] neg_hi:[1,0,0]
	v_pk_mul_f32 v[42:43], v[42:43], v[50:51] op_sel_hi:[1,0]
	v_pk_mul_f32 v[40:41], v[40:41], v[50:51] op_sel_hi:[1,0]
	v_pk_mul_f32 v[56:57], v[46:47], v[46:47]
	v_cndmask_b32_e32 v51, v52, v58, vcc
	v_cmp_gt_f32_e32 vcc, 0, v45
	v_pk_fma_f32 v[44:45], v[60:61], s[28:29], v[54:55] op_sel_hi:[1,0,0]
	v_lshlrev_b64 v[48:49], 12, v[154:155]
	v_cndmask_b32_e32 v58, v53, v59, vcc
	v_pk_mul_f32 v[52:53], v[56:57], s[40:41] op_sel_hi:[1,0]
	v_pk_fma_f32 v[44:45], v[60:61], v[44:45], s[34:35] op_sel_hi:[1,1,0]
	v_exp_f32_e32 v52, v52
	v_exp_f32_e32 v53, v53
	v_pk_fma_f32 v[44:45], v[60:61], v[44:45], s[36:37] op_sel_hi:[1,1,0]
	v_and_b32_e32 v57, 0x7fffffff, v41
	v_and_b32_e32 v56, 0x7fffffff, v40
	v_pk_fma_f32 v[44:45], v[60:61], v[44:45], s[38:39] op_sel_hi:[1,1,0]
	v_pk_fma_f32 v[56:57], v[56:57], s[26:27], 1.0 op_sel_hi:[1,0,0]
	v_pk_mul_f32 v[44:45], v[60:61], v[44:45]
	v_rcp_f32_e32 v56, v56
	v_rcp_f32_e32 v57, v57
	v_pk_mul_f32 v[44:45], v[52:53], v[44:45]
	v_cmp_gt_f32_e32 vcc, 0, v46
	v_pk_mul_f32 v[52:53], v[46:47], v[44:45]
	v_pk_fma_f32 v[44:45], v[46:47], v[44:45], v[46:47] neg_lo:[1,0,0] neg_hi:[1,0,0]
	v_lshl_add_u64 v[48:49], v[152:153], 0, v[48:49]
	v_cndmask_b32_e32 v59, v44, v52, vcc
	v_cmp_gt_f32_e32 vcc, 0, v47
	v_pk_mul_f32 v[46:47], v[40:41], v[40:41]
	s_nop 0
	v_cndmask_b32_e32 v60, v45, v53, vcc
	v_pk_fma_f32 v[44:45], v[56:57], s[28:29], v[54:55] op_sel_hi:[1,0,0]
	v_pk_mul_f32 v[46:47], v[46:47], s[40:41] op_sel_hi:[1,0]
	v_pk_fma_f32 v[44:45], v[56:57], v[44:45], s[34:35] op_sel_hi:[1,1,0]
	v_exp_f32_e32 v46, v46
	v_pk_fma_f32 v[44:45], v[56:57], v[44:45], s[36:37] op_sel_hi:[1,1,0]
	v_exp_f32_e32 v47, v47
	v_pk_fma_f32 v[44:45], v[56:57], v[44:45], s[38:39] op_sel_hi:[1,1,0]
	v_cmp_gt_f32_e32 vcc, 0, v40
	v_pk_mul_f32 v[44:45], v[56:57], v[44:45]
	v_and_b32_e32 v57, 0x7fffffff, v43
	v_and_b32_e32 v56, 0x7fffffff, v42
	v_pk_fma_f32 v[56:57], v[56:57], s[26:27], 1.0 op_sel_hi:[1,0,0]
	v_pk_mul_f32 v[44:45], v[46:47], v[44:45]
	v_rcp_f32_e32 v56, v56
	v_rcp_f32_e32 v57, v57
	v_pk_mul_f32 v[46:47], v[40:41], v[44:45]
	v_pk_fma_f32 v[44:45], v[40:41], v[44:45], v[40:41] neg_lo:[1,0,0] neg_hi:[1,0,0]
	v_pk_mul_f32 v[52:53], v[42:43], v[42:43]
	v_cndmask_b32_e32 v46, v44, v46, vcc
	v_cmp_gt_f32_e32 vcc, 0, v41
	v_pk_fma_f32 v[40:41], v[56:57], s[28:29], v[54:55] op_sel_hi:[1,0,0]
	s_nop 0
	v_cndmask_b32_e32 v47, v45, v47, vcc
	v_pk_mul_f32 v[44:45], v[52:53], s[40:41] op_sel_hi:[1,0]
	v_pk_fma_f32 v[40:41], v[56:57], v[40:41], s[34:35] op_sel_hi:[1,1,0]
	v_exp_f32_e32 v44, v44
	v_exp_f32_e32 v45, v45
	v_pk_fma_f32 v[40:41], v[56:57], v[40:41], s[36:37] op_sel_hi:[1,1,0]
	v_cmp_gt_f32_e32 vcc, 0, v42
	v_pk_fma_f32 v[40:41], v[56:57], v[40:41], s[38:39] op_sel_hi:[1,1,0]
	s_nop 0
	v_pk_mul_f32 v[40:41], v[56:57], v[40:41]
	s_nop 0
	v_pk_mul_f32 v[40:41], v[44:45], v[40:41]
	s_nop 0
	v_pk_mul_f32 v[44:45], v[42:43], v[40:41]
	v_pk_fma_f32 v[40:41], v[42:43], v[40:41], v[42:43] neg_lo:[1,0,0] neg_hi:[1,0,0]
	s_nop 0
	v_cndmask_b32_e32 v44, v40, v44, vcc
	v_cmp_gt_f32_e32 vcc, 0, v43
	v_cvt_pk_bf16_f32 v40, v51, v58
	s_nop 1
	v_cndmask_b32_e32 v43, v41, v45, vcc
	v_cvt_pk_bf16_f32 v41, v59, v60
	v_cvt_pk_bf16_f32 v42, v46, v47
	v_cvt_pk_bf16_f32 v43, v44, v43
	v_mov_b32_e32 v44, 0
	s_and_b64 vcc, exec, s[8:9]
	v_mov_b32_e32 v45, 0
	global_store_dwordx4 v[48:49], v[40:43], off
	s_cbranch_vccnz .LBB0_255
	v_and_b32_e32 v45, 16, v40
	v_and_b32_e32 v44, 0xffff0000, v40
	v_lshlrev_b32_e32 v53, 16, v41
	v_lshlrev_b32_e32 v52, 16, v42
	v_and_b32_e32 v46, 0xffff0000, v41
	v_mov_b32_e32 v47, v44
	v_pk_mov_b32 v[58:59], v[52:53], v[44:45] op_sel:[1,0]
	v_lshlrev_b32_e32 v40, 16, v40
	v_and_b32_e32 v54, 0xffff0000, v43
	v_mov_b32_e32 v55, v46
	v_and_b32_e32 v42, 0xffff0000, v42
	v_lshlrev_b32_e32 v56, 16, v43
	v_mov_b32_e32 v43, v53
	v_mov_b32_e32 v41, v46
	v_mov_b32_e32 v57, v46
	v_pk_add_f32 v[60:61], v[46:47], v[58:59]
	v_pk_mul_f32 v[46:47], v[46:47], v[58:59]
	v_pk_add_f32 v[44:45], v[40:41], v[44:45] op_sel_hi:[0,1]
	v_mov_b32_e32 v61, v47
	v_pk_add_f32 v[46:47], v[52:53], v[42:43]
	v_pk_mul_f32 v[58:59], v[52:53], v[52:53]
	v_mov_b32_e32 v43, v54
	v_mul_f32_e32 v45, v40, v40
	v_mov_b32_e32 v47, v59
	v_pk_add_f32 v[58:59], v[54:55], v[56:57]
	v_pk_mul_f32 v[40:41], v[54:55], v[40:41]
	v_mov_b32_e32 v53, v56
	v_pk_mul_f32 v[42:43], v[42:43], v[42:43]
	v_mov_b32_e32 v59, v41
	v_pk_fma_f32 v[42:43], v[52:53], v[52:53], v[42:43]
	v_pk_add_f32 v[44:45], v[44:45], v[60:61]
	v_pk_add_f32 v[40:41], v[46:47], v[58:59]
	v_pk_add_f32 v[42:43], v[42:43], v[42:43] op_sel_hi:[0,1]
	v_pk_add_f32 v[40:41], v[44:45], v[40:41]
	v_mov_b32_e32 v137, v43
	v_pk_add_f32 v[44:45], v[40:41], v[136:137]

.LBB0_259:
	s_nop 0
	v_add_f32_e32 v32, v183, v184
	v_fmamk_f32 v32, v32, 0x3a800000, v177
	v_mov_b64_e32 v[38:39], s[30:31]
	s_waitcnt lgkmcnt(1)
	s_waitcnt lgkmcnt(0)
	v_rsq_f32_e32 v34, v32
	s_nop 0
	v_pk_mul_f32 v[28:29], v[28:29], v[34:35] op_sel_hi:[1,0]
	v_pk_mul_f32 v[30:31], v[30:31], v[34:35] op_sel_hi:[1,0]
	v_and_b32_e32 v37, 0x7fffffff, v29
	v_and_b32_e32 v36, 0x7fffffff, v28
	v_pk_fma_f32 v[36:37], v[36:37], s[26:27], 1.0 op_sel_hi:[1,0,0]
	v_pk_mul_f32 v[42:43], v[28:29], v[28:29]
	v_rcp_f32_e32 v36, v36
	v_rcp_f32_e32 v37, v37
	v_pk_mul_f32 v[42:43], v[42:43], s[40:41] op_sel_hi:[1,0]
	v_and_b32_e32 v45, 0x7fffffff, v31
	v_exp_f32_e32 v42, v42
	v_pk_fma_f32 v[40:41], v[36:37], s[28:29], v[38:39] op_sel_hi:[1,0,0]
	v_exp_f32_e32 v43, v43
	v_pk_fma_f32 v[40:41], v[36:37], v[40:41], s[34:35] op_sel_hi:[1,1,0]
	v_and_b32_e32 v44, 0x7fffffff, v30
	v_pk_fma_f32 v[40:41], v[36:37], v[40:41], s[36:37] op_sel_hi:[1,1,0]
	v_pk_fma_f32 v[44:45], v[44:45], s[26:27], 1.0 op_sel_hi:[1,0,0]
	v_pk_fma_f32 v[40:41], v[36:37], v[40:41], s[38:39] op_sel_hi:[1,1,0]
	v_rcp_f32_e32 v44, v44
	v_pk_mul_f32 v[36:37], v[36:37], v[40:41]
	v_rcp_f32_e32 v45, v45
	v_pk_mul_f32 v[36:37], v[42:43], v[36:37]
	v_cmp_gt_f32_e32 vcc, 0, v28
	v_pk_mul_f32 v[42:43], v[28:29], v[36:37]
	v_pk_fma_f32 v[36:37], v[28:29], v[36:37], v[28:29] neg_lo:[1,0,0] neg_hi:[1,0,0]
	v_pk_mul_f32 v[26:27], v[26:27], v[34:35] op_sel_hi:[1,0]
	v_pk_mul_f32 v[24:25], v[24:25], v[34:35] op_sel_hi:[1,0]
	v_pk_mul_f32 v[40:41], v[30:31], v[30:31]
	v_cndmask_b32_e32 v35, v36, v42, vcc
	v_cmp_gt_f32_e32 vcc, 0, v29
	v_pk_fma_f32 v[28:29], v[44:45], s[28:29], v[38:39] op_sel_hi:[1,0,0]
	v_lshlrev_b64 v[32:33], 12, v[150:151]
	v_cndmask_b32_e32 v42, v37, v43, vcc
	v_pk_mul_f32 v[36:37], v[40:41], s[40:41] op_sel_hi:[1,0]
	v_pk_fma_f32 v[28:29], v[44:45], v[28:29], s[34:35] op_sel_hi:[1,1,0]
	v_exp_f32_e32 v36, v36
	v_exp_f32_e32 v37, v37
	v_pk_fma_f32 v[28:29], v[44:45], v[28:29], s[36:37] op_sel_hi:[1,1,0]
	v_and_b32_e32 v41, 0x7fffffff, v25
	v_and_b32_e32 v40, 0x7fffffff, v24
	v_pk_fma_f32 v[28:29], v[44:45], v[28:29], s[38:39] op_sel_hi:[1,1,0]
	v_pk_fma_f32 v[40:41], v[40:41], s[26:27], 1.0 op_sel_hi:[1,0,0]
	v_pk_mul_f32 v[28:29], v[44:45], v[28:29]
	v_rcp_f32_e32 v40, v40
	v_rcp_f32_e32 v41, v41
	v_pk_mul_f32 v[28:29], v[36:37], v[28:29]
	v_cmp_gt_f32_e32 vcc, 0, v30
	v_pk_mul_f32 v[36:37], v[30:31], v[28:29]
	v_pk_fma_f32 v[28:29], v[30:31], v[28:29], v[30:31] neg_lo:[1,0,0] neg_hi:[1,0,0]
	v_lshl_add_u64 v[32:33], v[152:153], 0, v[32:33]
	v_cndmask_b32_e32 v43, v28, v36, vcc
	v_cmp_gt_f32_e32 vcc, 0, v31
	v_pk_mul_f32 v[30:31], v[24:25], v[24:25]
	s_nop 0
	v_cndmask_b32_e32 v44, v29, v37, vcc
	v_pk_fma_f32 v[28:29], v[40:41], s[28:29], v[38:39] op_sel_hi:[1,0,0]
	v_pk_mul_f32 v[30:31], v[30:31], s[40:41] op_sel_hi:[1,0]
	v_pk_fma_f32 v[28:29], v[40:41], v[28:29], s[34:35] op_sel_hi:[1,1,0]
	v_exp_f32_e32 v30, v30
	v_pk_fma_f32 v[28:29], v[40:41], v[28:29], s[36:37] op_sel_hi:[1,1,0]
	v_exp_f32_e32 v31, v31
	v_pk_fma_f32 v[28:29], v[40:41], v[28:29], s[38:39] op_sel_hi:[1,1,0]
	v_cmp_gt_f32_e32 vcc, 0, v24
	v_pk_mul_f32 v[28:29], v[40:41], v[28:29]
	v_and_b32_e32 v41, 0x7fffffff, v27
	v_and_b32_e32 v40, 0x7fffffff, v26
	v_pk_fma_f32 v[40:41], v[40:41], s[26:27], 1.0 op_sel_hi:[1,0,0]
	v_pk_mul_f32 v[28:29], v[30:31], v[28:29]
	v_rcp_f32_e32 v40, v40
	v_rcp_f32_e32 v41, v41
	v_pk_mul_f32 v[30:31], v[24:25], v[28:29]
	v_pk_fma_f32 v[28:29], v[24:25], v[28:29], v[24:25] neg_lo:[1,0,0] neg_hi:[1,0,0]
	v_pk_mul_f32 v[36:37], v[26:27], v[26:27]
	v_cndmask_b32_e32 v30, v28, v30, vcc
	v_cmp_gt_f32_e32 vcc, 0, v25
	v_pk_fma_f32 v[24:25], v[40:41], s[28:29], v[38:39] op_sel_hi:[1,0,0]
	s_nop 0
	v_cndmask_b32_e32 v31, v29, v31, vcc
	v_pk_mul_f32 v[28:29], v[36:37], s[40:41] op_sel_hi:[1,0]
	v_pk_fma_f32 v[24:25], v[40:41], v[24:25], s[34:35] op_sel_hi:[1,1,0]
	v_exp_f32_e32 v28, v28
	v_exp_f32_e32 v29, v29
	v_pk_fma_f32 v[24:25], v[40:41], v[24:25], s[36:37] op_sel_hi:[1,1,0]
	v_cmp_gt_f32_e32 vcc, 0, v26
	v_pk_fma_f32 v[24:25], v[40:41], v[24:25], s[38:39] op_sel_hi:[1,1,0]
	s_nop 0
	v_pk_mul_f32 v[24:25], v[40:41], v[24:25]
	s_nop 0
	v_pk_mul_f32 v[24:25], v[28:29], v[24:25]
	s_nop 0
	v_pk_mul_f32 v[28:29], v[26:27], v[24:25]
	v_pk_fma_f32 v[24:25], v[26:27], v[24:25], v[26:27] neg_lo:[1,0,0] neg_hi:[1,0,0]
	s_nop 0
	v_cndmask_b32_e32 v28, v24, v28, vcc
	v_cmp_gt_f32_e32 vcc, 0, v27
	v_cvt_pk_bf16_f32 v24, v35, v42
	s_nop 1
	v_cndmask_b32_e32 v27, v25, v29, vcc
	v_cvt_pk_bf16_f32 v25, v43, v44
	v_cvt_pk_bf16_f32 v26, v30, v31
	v_cvt_pk_bf16_f32 v27, v28, v27
	v_mov_b32_e32 v28, 0
	s_and_b64 vcc, exec, s[8:9]
	v_mov_b32_e32 v29, 0
	global_store_dwordx4 v[32:33], v[24:27], off
	s_cbranch_vccnz .LBB0_261
	v_and_b32_e32 v29, 16, v24
	v_and_b32_e32 v28, 0xffff0000, v24
	v_lshlrev_b32_e32 v37, 16, v25
	v_lshlrev_b32_e32 v36, 16, v26
	v_and_b32_e32 v30, 0xffff0000, v25
	v_mov_b32_e32 v31, v28
	v_pk_mov_b32 v[42:43], v[36:37], v[28:29] op_sel:[1,0]
	v_lshlrev_b32_e32 v24, 16, v24
	v_and_b32_e32 v38, 0xffff0000, v27
	v_mov_b32_e32 v39, v30
	v_and_b32_e32 v26, 0xffff0000, v26
	v_lshlrev_b32_e32 v40, 16, v27
	v_mov_b32_e32 v27, v37
	v_mov_b32_e32 v25, v30
	v_mov_b32_e32 v41, v30
	v_pk_add_f32 v[44:45], v[30:31], v[42:43]
	v_pk_mul_f32 v[30:31], v[30:31], v[42:43]
	v_pk_add_f32 v[28:29], v[24:25], v[28:29] op_sel_hi:[0,1]
	v_mov_b32_e32 v45, v31
	v_pk_add_f32 v[30:31], v[36:37], v[26:27]
	v_pk_mul_f32 v[42:43], v[36:37], v[36:37]
	v_mov_b32_e32 v27, v38
	v_mul_f32_e32 v29, v24, v24
	v_mov_b32_e32 v31, v43
	v_pk_add_f32 v[42:43], v[38:39], v[40:41]
	v_pk_mul_f32 v[24:25], v[38:39], v[24:25]
	v_mov_b32_e32 v37, v40
	v_pk_mul_f32 v[26:27], v[26:27], v[26:27]
	v_mov_b32_e32 v43, v25
	v_pk_fma_f32 v[26:27], v[36:37], v[36:37], v[26:27]
	v_pk_add_f32 v[28:29], v[28:29], v[44:45]
	v_pk_add_f32 v[24:25], v[30:31], v[42:43]
	v_pk_add_f32 v[26:27], v[26:27], v[26:27] op_sel_hi:[0,1]
	v_pk_add_f32 v[24:25], v[28:29], v[24:25]
	v_mov_b32_e32 v137, v27
	v_pk_add_f32 v[28:29], v[24:25], v[136:137]

.LBB0_265:
	s_nop 0
	v_add_f32_e32 v16, v181, v182
	v_fmamk_f32 v16, v16, 0x3a800000, v177
	v_mov_b64_e32 v[22:23], s[30:31]
	s_waitcnt lgkmcnt(1)
	s_waitcnt lgkmcnt(0)
	v_rsq_f32_e32 v18, v16
	s_nop 0
	v_pk_mul_f32 v[12:13], v[12:13], v[18:19] op_sel_hi:[1,0]
	v_pk_mul_f32 v[14:15], v[14:15], v[18:19] op_sel_hi:[1,0]
	v_and_b32_e32 v21, 0x7fffffff, v13
	v_and_b32_e32 v20, 0x7fffffff, v12
	v_pk_fma_f32 v[20:21], v[20:21], s[26:27], 1.0 op_sel_hi:[1,0,0]
	v_pk_mul_f32 v[26:27], v[12:13], v[12:13]
	v_rcp_f32_e32 v20, v20
	v_rcp_f32_e32 v21, v21
	v_pk_mul_f32 v[26:27], v[26:27], s[40:41] op_sel_hi:[1,0]
	v_and_b32_e32 v29, 0x7fffffff, v15
	v_exp_f32_e32 v26, v26
	v_pk_fma_f32 v[24:25], v[20:21], s[28:29], v[22:23] op_sel_hi:[1,0,0]
	v_exp_f32_e32 v27, v27
	v_pk_fma_f32 v[24:25], v[20:21], v[24:25], s[34:35] op_sel_hi:[1,1,0]
	v_and_b32_e32 v28, 0x7fffffff, v14
	v_pk_fma_f32 v[24:25], v[20:21], v[24:25], s[36:37] op_sel_hi:[1,1,0]
	v_pk_fma_f32 v[28:29], v[28:29], s[26:27], 1.0 op_sel_hi:[1,0,0]
	v_pk_fma_f32 v[24:25], v[20:21], v[24:25], s[38:39] op_sel_hi:[1,1,0]
	v_rcp_f32_e32 v28, v28
	v_pk_mul_f32 v[20:21], v[20:21], v[24:25]
	v_rcp_f32_e32 v29, v29
	v_pk_mul_f32 v[20:21], v[26:27], v[20:21]
	v_cmp_gt_f32_e32 vcc, 0, v12
	v_pk_mul_f32 v[26:27], v[12:13], v[20:21]
	v_pk_fma_f32 v[20:21], v[12:13], v[20:21], v[12:13] neg_lo:[1,0,0] neg_hi:[1,0,0]
	v_pk_mul_f32 v[10:11], v[10:11], v[18:19] op_sel_hi:[1,0]
	v_pk_mul_f32 v[8:9], v[8:9], v[18:19] op_sel_hi:[1,0]
	v_pk_mul_f32 v[24:25], v[14:15], v[14:15]
	v_cndmask_b32_e32 v19, v20, v26, vcc
	v_cmp_gt_f32_e32 vcc, 0, v13
	v_pk_fma_f32 v[12:13], v[28:29], s[28:29], v[22:23] op_sel_hi:[1,0,0]
	v_lshlrev_b64 v[16:17], 12, v[148:149]
	v_cndmask_b32_e32 v26, v21, v27, vcc
	v_pk_mul_f32 v[20:21], v[24:25], s[40:41] op_sel_hi:[1,0]
	v_pk_fma_f32 v[12:13], v[28:29], v[12:13], s[34:35] op_sel_hi:[1,1,0]
	v_exp_f32_e32 v20, v20
	v_exp_f32_e32 v21, v21
	v_pk_fma_f32 v[12:13], v[28:29], v[12:13], s[36:37] op_sel_hi:[1,1,0]
	v_and_b32_e32 v25, 0x7fffffff, v9
	v_and_b32_e32 v24, 0x7fffffff, v8
	v_pk_fma_f32 v[12:13], v[28:29], v[12:13], s[38:39] op_sel_hi:[1,1,0]
	v_pk_fma_f32 v[24:25], v[24:25], s[26:27], 1.0 op_sel_hi:[1,0,0]
	v_pk_mul_f32 v[12:13], v[28:29], v[12:13]
	v_rcp_f32_e32 v24, v24
	v_rcp_f32_e32 v25, v25
	v_pk_mul_f32 v[12:13], v[20:21], v[12:13]
	v_cmp_gt_f32_e32 vcc, 0, v14
	v_pk_mul_f32 v[20:21], v[14:15], v[12:13]
	v_pk_fma_f32 v[12:13], v[14:15], v[12:13], v[14:15] neg_lo:[1,0,0] neg_hi:[1,0,0]
	v_lshl_add_u64 v[16:17], v[152:153], 0, v[16:17]
	v_cndmask_b32_e32 v27, v12, v20, vcc
	v_cmp_gt_f32_e32 vcc, 0, v15
	v_pk_mul_f32 v[14:15], v[8:9], v[8:9]
	s_nop 0
	v_cndmask_b32_e32 v28, v13, v21, vcc
	v_pk_fma_f32 v[12:13], v[24:25], s[28:29], v[22:23] op_sel_hi:[1,0,0]
	v_pk_mul_f32 v[14:15], v[14:15], s[40:41] op_sel_hi:[1,0]
	v_pk_fma_f32 v[12:13], v[24:25], v[12:13], s[34:35] op_sel_hi:[1,1,0]
	v_exp_f32_e32 v14, v14
	v_pk_fma_f32 v[12:13], v[24:25], v[12:13], s[36:37] op_sel_hi:[1,1,0]
	v_exp_f32_e32 v15, v15
	v_pk_fma_f32 v[12:13], v[24:25], v[12:13], s[38:39] op_sel_hi:[1,1,0]
	v_cmp_gt_f32_e32 vcc, 0, v8
	v_pk_mul_f32 v[12:13], v[24:25], v[12:13]
	v_and_b32_e32 v25, 0x7fffffff, v11
	v_and_b32_e32 v24, 0x7fffffff, v10
	v_pk_fma_f32 v[24:25], v[24:25], s[26:27], 1.0 op_sel_hi:[1,0,0]
	v_pk_mul_f32 v[12:13], v[14:15], v[12:13]
	v_rcp_f32_e32 v24, v24
	v_rcp_f32_e32 v25, v25
	v_pk_mul_f32 v[14:15], v[8:9], v[12:13]
	v_pk_fma_f32 v[12:13], v[8:9], v[12:13], v[8:9] neg_lo:[1,0,0] neg_hi:[1,0,0]
	v_pk_mul_f32 v[20:21], v[10:11], v[10:11]
	v_cndmask_b32_e32 v14, v12, v14, vcc
	v_cmp_gt_f32_e32 vcc, 0, v9
	v_pk_fma_f32 v[8:9], v[24:25], s[28:29], v[22:23] op_sel_hi:[1,0,0]
	s_nop 0
	v_cndmask_b32_e32 v15, v13, v15, vcc
	v_pk_mul_f32 v[12:13], v[20:21], s[40:41] op_sel_hi:[1,0]
	v_pk_fma_f32 v[8:9], v[24:25], v[8:9], s[34:35] op_sel_hi:[1,1,0]
	v_exp_f32_e32 v12, v12
	v_exp_f32_e32 v13, v13
	v_pk_fma_f32 v[8:9], v[24:25], v[8:9], s[36:37] op_sel_hi:[1,1,0]
	v_cmp_gt_f32_e32 vcc, 0, v10
	v_pk_fma_f32 v[8:9], v[24:25], v[8:9], s[38:39] op_sel_hi:[1,1,0]
	s_nop 0
	v_pk_mul_f32 v[8:9], v[24:25], v[8:9]
	s_nop 0
	v_pk_mul_f32 v[8:9], v[12:13], v[8:9]
	s_nop 0
	v_pk_mul_f32 v[12:13], v[10:11], v[8:9]
	v_pk_fma_f32 v[8:9], v[10:11], v[8:9], v[10:11] neg_lo:[1,0,0] neg_hi:[1,0,0]
	s_nop 0
	v_cndmask_b32_e32 v12, v8, v12, vcc
	v_cmp_gt_f32_e32 vcc, 0, v11
	v_cvt_pk_bf16_f32 v8, v19, v26
	s_nop 1
	v_cndmask_b32_e32 v11, v9, v13, vcc
	v_cvt_pk_bf16_f32 v9, v27, v28
	v_cvt_pk_bf16_f32 v10, v14, v15
	v_cvt_pk_bf16_f32 v11, v12, v11
	v_mov_b32_e32 v12, 0
	s_and_b64 vcc, exec, s[8:9]
	v_mov_b32_e32 v13, 0
	global_store_dwordx4 v[16:17], v[8:11], off
	s_cbranch_vccnz .LBB0_267
	v_and_b32_e32 v13, 16, v8
	v_and_b32_e32 v12, 0xffff0000, v8
	v_lshlrev_b32_e32 v21, 16, v9
	v_lshlrev_b32_e32 v20, 16, v10
	v_and_b32_e32 v14, 0xffff0000, v9
	v_mov_b32_e32 v15, v12
	v_pk_mov_b32 v[26:27], v[20:21], v[12:13] op_sel:[1,0]
	v_lshlrev_b32_e32 v8, 16, v8
	v_and_b32_e32 v22, 0xffff0000, v11
	v_mov_b32_e32 v23, v14
	v_and_b32_e32 v10, 0xffff0000, v10
	v_lshlrev_b32_e32 v24, 16, v11
	v_mov_b32_e32 v11, v21
	v_mov_b32_e32 v9, v14
	v_mov_b32_e32 v25, v14
	v_pk_add_f32 v[28:29], v[14:15], v[26:27]
	v_pk_mul_f32 v[14:15], v[14:15], v[26:27]
	v_pk_add_f32 v[12:13], v[8:9], v[12:13] op_sel_hi:[0,1]
	v_mov_b32_e32 v29, v15
	v_pk_add_f32 v[14:15], v[20:21], v[10:11]
	v_pk_mul_f32 v[26:27], v[20:21], v[20:21]
	v_mov_b32_e32 v11, v22
	v_mul_f32_e32 v13, v8, v8
	v_mov_b32_e32 v15, v27
	v_pk_add_f32 v[26:27], v[22:23], v[24:25]
	v_pk_mul_f32 v[8:9], v[22:23], v[8:9]
	v_mov_b32_e32 v21, v24
	v_pk_mul_f32 v[10:11], v[10:11], v[10:11]
	v_mov_b32_e32 v27, v9
	v_pk_fma_f32 v[10:11], v[20:21], v[20:21], v[10:11]
	v_pk_add_f32 v[12:13], v[12:13], v[28:29]
	v_pk_add_f32 v[8:9], v[14:15], v[26:27]
	v_pk_add_f32 v[10:11], v[10:11], v[10:11] op_sel_hi:[0,1]
	v_pk_add_f32 v[8:9], v[12:13], v[8:9]
	v_mov_b32_e32 v137, v11
	v_pk_add_f32 v[12:13], v[8:9], v[136:137]

.LBB0_648:
	s_or_b64 exec, exec, s[12:13]
	s_waitcnt lgkmcnt(7)
	v_add_f32_e32 v144, v144, v180
	v_fmamk_f32 v144, v144, 0x3a800000, v195
	v_rsq_f32_e32 v180, v144
	s_nop 0
	v_pk_mul_f32 v[184:185], v[122:123], v[180:181] op_sel_hi:[1,0]
	v_cndmask_b32_e64 v122, 0, 1, s[22:23]
	v_pk_mul_f32 v[126:127], v[126:127], v[180:181] op_sel_hi:[1,0]
	v_pk_mul_f32 v[182:183], v[124:125], v[180:181] op_sel_hi:[1,0]
	v_cmp_ne_u32_e64 s[12:13], 1, v122
	s_andn2_b64 vcc, exec, s[22:23]
	v_pk_mul_f32 v[186:187], v[120:121], v[180:181] op_sel_hi:[1,0]
	s_cbranch_vccnz .LBB0_650
	ds_bpermute_b32 v120, v198, v182
	ds_bpermute_b32 v121, v198, v183
	ds_bpermute_b32 v122, v198, v186
	ds_bpermute_b32 v124, v198, v126
	ds_bpermute_b32 v125, v198, v127
	ds_bpermute_b32 v123, v198, v187
	ds_bpermute_b32 v216, v198, v184
	ds_bpermute_b32 v217, v198, v185
	s_waitcnt lgkmcnt(6)
	v_pk_mul_f32 v[120:121], v[176:177], v[120:121]
	s_waitcnt lgkmcnt(3)
	v_pk_mul_f32 v[124:125], v[178:179], v[124:125]
	s_waitcnt vmcnt(1)
	v_pk_fma_f32 v[182:183], v[182:183], v[132:133], v[120:121]
	s_waitcnt lgkmcnt(2)
	v_pk_mul_f32 v[120:121], v[174:175], v[122:123]
	s_waitcnt lgkmcnt(0)
	v_pk_mul_f32 v[122:123], v[172:173], v[216:217]
	v_pk_fma_f32 v[126:127], v[126:127], v[134:135], v[124:125]
	s_waitcnt vmcnt(0)
	v_pk_fma_f32 v[184:185], v[184:185], v[130:131], v[122:123]
	v_pk_fma_f32 v[186:187], v[186:187], v[128:129], v[120:121]

.LBB0_654:
	s_or_b64 exec, exec, s[4:5]
	s_waitcnt lgkmcnt(6)
	v_add_f32_e32 v132, v213, v214
	v_fmamk_f32 v132, v132, 0x3a800000, v195
	v_rsq_f32_e32 v132, v132
	s_nop 0
	v_pk_mul_f32 v[110:111], v[110:111], v[132:133] op_sel_hi:[1,0]
	v_pk_mul_f32 v[108:109], v[108:109], v[132:133] op_sel_hi:[1,0]
	v_pk_mul_f32 v[134:135], v[106:107], v[132:133] op_sel_hi:[1,0]
	s_and_b64 vcc, exec, s[12:13]
	v_pk_mul_f32 v[170:171], v[104:105], v[132:133] op_sel_hi:[1,0]
	s_cbranch_vccnz .LBB0_656
	ds_bpermute_b32 v104, v198, v108
	ds_bpermute_b32 v105, v198, v109
	ds_bpermute_b32 v106, v198, v170
	ds_bpermute_b32 v172, v198, v110
	ds_bpermute_b32 v173, v198, v111
	ds_bpermute_b32 v107, v198, v171
	ds_bpermute_b32 v174, v198, v134
	ds_bpermute_b32 v175, v198, v135
	s_waitcnt lgkmcnt(6)
	v_pk_mul_f32 v[104:105], v[128:129], v[104:105]
	s_waitcnt lgkmcnt(3)
	v_pk_mul_f32 v[172:173], v[130:131], v[172:173]
	s_waitcnt vmcnt(1)
	v_pk_fma_f32 v[108:109], v[108:109], v[116:117], v[104:105]
	s_waitcnt lgkmcnt(2)
	v_pk_mul_f32 v[104:105], v[126:127], v[106:107]
	s_waitcnt lgkmcnt(0)
	v_pk_mul_f32 v[106:107], v[124:125], v[174:175]
	v_pk_fma_f32 v[110:111], v[110:111], v[118:119], v[172:173]
	s_waitcnt vmcnt(0)
	v_pk_fma_f32 v[134:135], v[134:135], v[114:115], v[106:107]
	v_pk_fma_f32 v[170:171], v[170:171], v[112:113], v[104:105]

.LBB0_660:
	s_or_b64 exec, exec, s[4:5]
	s_waitcnt vmcnt(2) lgkmcnt(5)
	v_add_f32_e32 v112, v211, v212
	v_fmamk_f32 v112, v112, 0x3a800000, v195
	v_rsq_f32_e32 v112, v112
	s_nop 0
	v_pk_mul_f32 v[94:95], v[94:95], v[112:113] op_sel_hi:[1,0]
	v_pk_mul_f32 v[92:93], v[92:93], v[112:113] op_sel_hi:[1,0]
	v_pk_mul_f32 v[114:115], v[90:91], v[112:113] op_sel_hi:[1,0]
	s_and_b64 vcc, exec, s[12:13]
	v_pk_mul_f32 v[116:117], v[88:89], v[112:113] op_sel_hi:[1,0]
	s_cbranch_vccnz .LBB0_662
	ds_bpermute_b32 v88, v198, v92
	ds_bpermute_b32 v89, v198, v93
	ds_bpermute_b32 v90, v198, v116
	ds_bpermute_b32 v118, v198, v94
	ds_bpermute_b32 v119, v198, v95
	ds_bpermute_b32 v91, v198, v117
	ds_bpermute_b32 v124, v198, v114
	ds_bpermute_b32 v125, v198, v115
	s_waitcnt lgkmcnt(6)
	v_pk_mul_f32 v[88:89], v[108:109], v[88:89]
	s_waitcnt lgkmcnt(3)
	v_pk_mul_f32 v[118:119], v[110:111], v[118:119]
	s_waitcnt vmcnt(1)
	v_pk_fma_f32 v[92:93], v[92:93], v[100:101], v[88:89]
	s_waitcnt lgkmcnt(2)
	v_pk_mul_f32 v[88:89], v[106:107], v[90:91]
	s_waitcnt lgkmcnt(0)
	v_pk_mul_f32 v[90:91], v[104:105], v[124:125]
	v_pk_fma_f32 v[94:95], v[94:95], v[102:103], v[118:119]
	s_waitcnt vmcnt(0)
	v_pk_fma_f32 v[114:115], v[114:115], v[98:99], v[90:91]
	v_pk_fma_f32 v[116:117], v[116:117], v[96:97], v[88:89]

.LBB0_666:
	s_or_b64 exec, exec, s[4:5]
	s_waitcnt vmcnt(2) lgkmcnt(4)
	v_add_f32_e32 v96, v209, v210
	v_fmamk_f32 v96, v96, 0x3a800000, v195
	v_rsq_f32_e32 v96, v96
	s_nop 0
	v_pk_mul_f32 v[78:79], v[78:79], v[96:97] op_sel_hi:[1,0]
	v_pk_mul_f32 v[76:77], v[76:77], v[96:97] op_sel_hi:[1,0]
	v_pk_mul_f32 v[98:99], v[74:75], v[96:97] op_sel_hi:[1,0]
	s_and_b64 vcc, exec, s[12:13]
	v_pk_mul_f32 v[100:101], v[72:73], v[96:97] op_sel_hi:[1,0]
	s_cbranch_vccnz .LBB0_668
	ds_bpermute_b32 v72, v198, v76
	ds_bpermute_b32 v73, v198, v77
	ds_bpermute_b32 v74, v198, v100
	ds_bpermute_b32 v102, v198, v78
	ds_bpermute_b32 v103, v198, v79
	ds_bpermute_b32 v75, v198, v101
	ds_bpermute_b32 v104, v198, v98
	ds_bpermute_b32 v105, v198, v99
	s_waitcnt lgkmcnt(6)
	v_pk_mul_f32 v[72:73], v[92:93], v[72:73]
	s_waitcnt lgkmcnt(3)
	v_pk_mul_f32 v[102:103], v[94:95], v[102:103]
	s_waitcnt vmcnt(1)
	v_pk_fma_f32 v[76:77], v[76:77], v[84:85], v[72:73]
	s_waitcnt lgkmcnt(2)
	v_pk_mul_f32 v[72:73], v[90:91], v[74:75]
	s_waitcnt lgkmcnt(0)
	v_pk_mul_f32 v[74:75], v[88:89], v[104:105]
	v_pk_fma_f32 v[78:79], v[78:79], v[86:87], v[102:103]
	s_waitcnt vmcnt(0)
	v_pk_fma_f32 v[98:99], v[98:99], v[82:83], v[74:75]
	v_pk_fma_f32 v[100:101], v[100:101], v[80:81], v[72:73]

.LBB0_672:
	s_or_b64 exec, exec, s[4:5]
	s_waitcnt vmcnt(2) lgkmcnt(3)
	v_add_f32_e32 v80, v207, v208
	v_fmamk_f32 v80, v80, 0x3a800000, v195
	v_rsq_f32_e32 v80, v80
	s_nop 0
	v_pk_mul_f32 v[62:63], v[62:63], v[80:81] op_sel_hi:[1,0]
	v_pk_mul_f32 v[60:61], v[60:61], v[80:81] op_sel_hi:[1,0]
	v_pk_mul_f32 v[82:83], v[58:59], v[80:81] op_sel_hi:[1,0]
	s_and_b64 vcc, exec, s[12:13]
	v_pk_mul_f32 v[84:85], v[56:57], v[80:81] op_sel_hi:[1,0]
	s_cbranch_vccnz .LBB0_674
	ds_bpermute_b32 v56, v198, v60
	ds_bpermute_b32 v57, v198, v61
	ds_bpermute_b32 v58, v198, v84
	ds_bpermute_b32 v86, v198, v62
	ds_bpermute_b32 v87, v198, v63
	ds_bpermute_b32 v59, v198, v85
	ds_bpermute_b32 v88, v198, v82
	ds_bpermute_b32 v89, v198, v83
	s_waitcnt lgkmcnt(6)
	v_pk_mul_f32 v[56:57], v[76:77], v[56:57]
	s_waitcnt lgkmcnt(3)
	v_pk_mul_f32 v[86:87], v[78:79], v[86:87]
	s_waitcnt vmcnt(1)
	v_pk_fma_f32 v[60:61], v[60:61], v[68:69], v[56:57]
	s_waitcnt lgkmcnt(2)
	v_pk_mul_f32 v[56:57], v[74:75], v[58:59]
	s_waitcnt lgkmcnt(0)
	v_pk_mul_f32 v[58:59], v[72:73], v[88:89]
	v_pk_fma_f32 v[62:63], v[62:63], v[70:71], v[86:87]
	s_waitcnt vmcnt(0)
	v_pk_fma_f32 v[82:83], v[82:83], v[66:67], v[58:59]
	v_pk_fma_f32 v[84:85], v[84:85], v[64:65], v[56:57]

.LBB0_678:
	s_or_b64 exec, exec, s[4:5]
	s_waitcnt vmcnt(2) lgkmcnt(2)
	v_add_f32_e32 v64, v205, v206
	v_fmamk_f32 v64, v64, 0x3a800000, v195
	v_rsq_f32_e32 v64, v64
	s_nop 0
	v_pk_mul_f32 v[46:47], v[46:47], v[64:65] op_sel_hi:[1,0]
	v_pk_mul_f32 v[44:45], v[44:45], v[64:65] op_sel_hi:[1,0]
	v_pk_mul_f32 v[66:67], v[42:43], v[64:65] op_sel_hi:[1,0]
	s_and_b64 vcc, exec, s[12:13]
	v_pk_mul_f32 v[68:69], v[40:41], v[64:65] op_sel_hi:[1,0]
	s_cbranch_vccnz .LBB0_680
	ds_bpermute_b32 v40, v198, v44
	ds_bpermute_b32 v41, v198, v45
	ds_bpermute_b32 v42, v198, v68
	ds_bpermute_b32 v70, v198, v46
	ds_bpermute_b32 v71, v198, v47
	ds_bpermute_b32 v43, v198, v69
	ds_bpermute_b32 v72, v198, v66
	ds_bpermute_b32 v73, v198, v67
	s_waitcnt lgkmcnt(6)
	v_pk_mul_f32 v[40:41], v[60:61], v[40:41]
	s_waitcnt lgkmcnt(3)
	v_pk_mul_f32 v[70:71], v[62:63], v[70:71]
	s_waitcnt vmcnt(1)
	v_pk_fma_f32 v[44:45], v[44:45], v[52:53], v[40:41]
	s_waitcnt lgkmcnt(2)
	v_pk_mul_f32 v[40:41], v[58:59], v[42:43]
	s_waitcnt lgkmcnt(0)
	v_pk_mul_f32 v[42:43], v[56:57], v[72:73]
	v_pk_fma_f32 v[46:47], v[46:47], v[54:55], v[70:71]
	s_waitcnt vmcnt(0)
	v_pk_fma_f32 v[66:67], v[66:67], v[50:51], v[42:43]
	v_pk_fma_f32 v[68:69], v[68:69], v[48:49], v[40:41]

.LBB0_684:
	s_or_b64 exec, exec, s[4:5]
	s_waitcnt vmcnt(2) lgkmcnt(1)
	v_add_f32_e32 v48, v201, v204
	v_fmamk_f32 v48, v48, 0x3a800000, v195
	v_rsq_f32_e32 v48, v48
	s_nop 0
	v_pk_mul_f32 v[30:31], v[30:31], v[48:49] op_sel_hi:[1,0]
	v_pk_mul_f32 v[28:29], v[28:29], v[48:49] op_sel_hi:[1,0]
	v_pk_mul_f32 v[50:51], v[26:27], v[48:49] op_sel_hi:[1,0]
	s_and_b64 vcc, exec, s[12:13]
	v_pk_mul_f32 v[52:53], v[24:25], v[48:49] op_sel_hi:[1,0]
	s_cbranch_vccnz .LBB0_686
	ds_bpermute_b32 v24, v198, v28
	ds_bpermute_b32 v25, v198, v29
	ds_bpermute_b32 v26, v198, v52
	ds_bpermute_b32 v54, v198, v30
	ds_bpermute_b32 v55, v198, v31
	ds_bpermute_b32 v27, v198, v53
	ds_bpermute_b32 v56, v198, v50
	ds_bpermute_b32 v57, v198, v51
	s_waitcnt lgkmcnt(6)
	v_pk_mul_f32 v[24:25], v[44:45], v[24:25]
	s_waitcnt lgkmcnt(3)
	v_pk_mul_f32 v[54:55], v[46:47], v[54:55]
	s_waitcnt vmcnt(1)
	v_pk_fma_f32 v[28:29], v[28:29], v[36:37], v[24:25]
	s_waitcnt lgkmcnt(2)
	v_pk_mul_f32 v[24:25], v[42:43], v[26:27]
	s_waitcnt lgkmcnt(0)
	v_pk_mul_f32 v[26:27], v[40:41], v[56:57]
	v_pk_fma_f32 v[30:31], v[30:31], v[38:39], v[54:55]
	s_waitcnt vmcnt(0)
	v_pk_fma_f32 v[50:51], v[50:51], v[34:35], v[26:27]
	v_pk_fma_f32 v[52:53], v[52:53], v[32:33], v[24:25]

.LBB0_690:
	s_or_b64 exec, exec, s[4:5]
	s_waitcnt vmcnt(2) lgkmcnt(0)
	v_add_f32_e32 v32, v199, v200
	v_fmamk_f32 v32, v32, 0x3a800000, v195
	v_rsq_f32_e32 v32, v32
	s_nop 0
	v_pk_mul_f32 v[14:15], v[14:15], v[32:33] op_sel_hi:[1,0]
	v_pk_mul_f32 v[12:13], v[12:13], v[32:33] op_sel_hi:[1,0]
	v_pk_mul_f32 v[34:35], v[10:11], v[32:33] op_sel_hi:[1,0]
	s_and_b64 vcc, exec, s[12:13]
	v_pk_mul_f32 v[36:37], v[8:9], v[32:33] op_sel_hi:[1,0]
	s_cbranch_vccnz .LBB0_692
	ds_bpermute_b32 v8, v198, v12
	ds_bpermute_b32 v9, v198, v13
	ds_bpermute_b32 v10, v198, v36
	ds_bpermute_b32 v38, v198, v14
	ds_bpermute_b32 v39, v198, v15
	ds_bpermute_b32 v11, v198, v37
	ds_bpermute_b32 v40, v198, v34
	ds_bpermute_b32 v41, v198, v35
	s_waitcnt lgkmcnt(6)
	v_pk_mul_f32 v[8:9], v[28:29], v[8:9]
	s_waitcnt lgkmcnt(3)
	v_pk_mul_f32 v[38:39], v[30:31], v[38:39]
	s_waitcnt vmcnt(1)
	v_pk_fma_f32 v[12:13], v[12:13], v[20:21], v[8:9]
	s_waitcnt lgkmcnt(2)
	v_pk_mul_f32 v[8:9], v[26:27], v[10:11]
	s_waitcnt lgkmcnt(0)
	v_pk_mul_f32 v[10:11], v[24:25], v[40:41]
	v_pk_fma_f32 v[14:15], v[14:15], v[22:23], v[38:39]
	s_waitcnt vmcnt(0)
	v_pk_fma_f32 v[34:35], v[34:35], v[18:19], v[10:11]
	v_pk_fma_f32 v[36:37], v[36:37], v[16:17], v[8:9]
